# first-barrier census: 16 counter loads issued back to back (one wait); streamed sample k-loop (per-pair counted waits, slots re-issued at once); leader prepares announce address under its writeback
# speedup vs baseline: 1.0044x; 1.0044x over previous
; template <bool GATE>
; __device__ __forceinline__ void sample_gemm_res(LAS unsigned char* lds, const bf16* Amat, const bf16* Bt, const bf16* Hin, bf16* Hout, float* rss_out, const bf16* PP, const float* rss_in, int bid, int tid) {
;     ...
;   for (int tile = bid; tile < 256; tile += (int)gridDim.x) {
;     const int m0 = TP + (tile & 7) * 64, n0 = (tile >> 3) * 64;
;     const bf16x8* ap = (const bf16x8*)(Amat + (size_t)(m0 + lr) * 2048 + wave * 256 + 8 * kg);
;     const bf16x8* bp = (const bf16x8*)(Bt + (size_t)(n0 + lr) * 2048 + wave * 256 + 8 * kg);
;     const int erow = m0 + (tid >> 3); const size_t ep = (size_t)erow * 2048 + n0 + (tid & 7) * 8;
;     const u32x4 hw = *(const u32x4*)(Hin + ep); u32x4 pw = (u32x4){0u, 0u, 0u, 0u}; float rsi = 0.f; if (GATE) { pw = *(const u32x4*)(PP + ep); rsi = rss_in[erow]; }
;     f32x4m acc[4][4];
; #pragma unroll
;     for (int mi = 0; mi < 4; ++mi)
; #pragma unroll
;         for (int ni = 0; ni < 4; ++ni) acc[mi][ni] = (f32x4m){0.f, 0.f, 0.f, 0.f};
; #pragma unroll 2
;     for (int ks = 0; ks < 8; ++ks) { bf16x8 a[4], b[4];
; #pragma unroll
;         for (int q = 0; q < 4; ++q) { a[q] = ap[(size_t)q * 16 * 256 + ks * 4]; b[q] = bp[(size_t)q * 16 * 256 + ks * 4]; }
; #pragma unroll
;         for (int mi = 0; mi < 4; ++mi)
; #pragma unroll
;             for (int ni = 0; ni < 4; ++ni) acc[mi][ni] = __builtin_amdgcn_mfma_f32_16x16x32_bf16(a[mi], b[ni], acc[mi][ni], 0, 0, 0); }
.LBB0_67:
	s_lshl_b32 s0, s6, 6
	s_and_b32 s1, s0, 0x1c0
	v_add_u32_e32 v0, s1, v88
	s_lshl_b32 s0, s6, 3
	v_add_u32_e32 v80, 0x2000, v0
	s_andn2_b32 s0, s0, 63
	v_ashrrev_i32_e32 v81, 31, v80
	v_lshlrev_b64 v[2:3], 11, v[80:81]
	s_ashr_i32 s1, s0, 31
	v_lshl_add_u64 v[82:83], v[2:3], 0, s[0:1]
	v_or_b32_e32 v82, v82, v74
	v_lshlrev_b64 v[2:3], 1, v[82:83]
	v_lshl_add_u64 v[4:5], s[46:47], 0, v[2:3]
	v_lshl_add_u64 v[2:3], s[52:53], 0, v[2:3]
	v_lshl_add_u64 v[10:11], v[80:81], 2, s[54:55]
	global_load_dwordx4 v[6:9], v[4:5], off
	s_nop 0
	global_load_dwordx4 v[2:5], v[2:3], off
	s_and_b32 s0, s3, 0xffffffc0
	global_load_dword v100, v[10:11], off
	v_or_b32_e32 v10, s0, v75
	v_ashrrev_i32_e32 v11, 31, v10
	v_lshlrev_b64 v[10:11], 12, v[10:11]
	s_and_b32 s0, s2, 0x1c0
	v_lshl_add_u64 v[84:85], v[76:77], 0, v[10:11]
	v_add_lshl_u32 v0, v95, s0, 12
	v_mov_b32_e32 v10, 0
	v_lshl_add_u64 v[86:87], v[78:79], 0, v[0:1]
	s_mov_b64 s[4:5], 0
	v_mov_b32_e32 v11, v10
	v_mov_b32_e32 v12, v10
	v_mov_b32_e32 v13, v10
	v_mov_b32_e32 v14, v10
	v_mov_b32_e32 v15, v10
	v_mov_b32_e32 v16, v10
	v_mov_b32_e32 v17, v10
	v_mov_b32_e32 v18, v10
	v_mov_b32_e32 v19, v10
	v_mov_b32_e32 v20, v10
	v_mov_b32_e32 v21, v10
	v_mov_b32_e32 v22, v10
	v_mov_b32_e32 v23, v10
	v_mov_b32_e32 v24, v10
	v_mov_b32_e32 v25, v10
	v_mov_b32_e32 v26, v10
	v_mov_b32_e32 v27, v10
	v_mov_b32_e32 v28, v10
	v_mov_b32_e32 v29, v10
	v_mov_b32_e32 v34, v10
	v_mov_b32_e32 v35, v10
	v_mov_b32_e32 v36, v10
	v_mov_b32_e32 v37, v10
	v_mov_b32_e32 v30, v10
	v_mov_b32_e32 v31, v10
	v_mov_b32_e32 v32, v10
	v_mov_b32_e32 v33, v10
	v_mov_b32_e32 v38, v10
	v_mov_b32_e32 v39, v10
	v_mov_b32_e32 v40, v10
	v_mov_b32_e32 v41, v10
	v_mov_b32_e32 v42, v10
	v_mov_b32_e32 v43, v10
	v_mov_b32_e32 v44, v10
	v_mov_b32_e32 v45, v10
	v_mov_b32_e32 v50, v10
	v_mov_b32_e32 v51, v10
	v_mov_b32_e32 v52, v10
	v_mov_b32_e32 v53, v10
	v_mov_b32_e32 v46, v10
	v_mov_b32_e32 v47, v10
	v_mov_b32_e32 v48, v10
	v_mov_b32_e32 v49, v10
	v_mov_b32_e32 v58, v10
	v_mov_b32_e32 v59, v10
	v_mov_b32_e32 v60, v10
	v_mov_b32_e32 v61, v10
	v_mov_b32_e32 v54, v10
	v_mov_b32_e32 v55, v10
	v_mov_b32_e32 v56, v10
	v_mov_b32_e32 v57, v10
	v_mov_b32_e32 v66, v10
	v_mov_b32_e32 v67, v10
	v_mov_b32_e32 v68, v10
	v_mov_b32_e32 v69, v10
	v_mov_b32_e32 v62, v10
	v_mov_b32_e32 v63, v10
	v_mov_b32_e32 v64, v10
	v_mov_b32_e32 v65, v10
	v_mov_b32_e32 v70, v10
	v_mov_b32_e32 v71, v10
	v_mov_b32_e32 v72, v10
	v_mov_b32_e32 v73, v10
	v_readfirstlane_b32 s8, v86
	v_readfirstlane_b32 s9, v87
	v_readfirstlane_b32 s10, v84
	v_readfirstlane_b32 s11, v85
	s_add_u32 s8, s8, 0x22200000
	s_addc_u32 s9, s9, 0
	s_add_u32 s10, s10, 0x8200000
	s_addc_u32 s11, s11, 0
	v_lshrrev_b32_e32 v212, 3, v216
	v_and_b32_e32 v213, 7, v216
	v_xor_b32_e32 v213, v213, v212
	v_lshlrev_b32_e32 v213, 4, v213
	v_lshl_or_b32 v248, v212, 12, v213
	v_and_b32_e32 v212, 15, v216
	v_lshrrev_b32_e32 v213, 4, v216
	v_and_b32_e32 v249, 7, v212
	v_xor_b32_e32 v213, v213, v249
	v_lshlrev_b32_e32 v213, 4, v213
	v_lshl_or_b32 v249, v212, 7, v213
	v_lshrrev_b32_e32 v212, 6, v183
	s_nop 0
	v_readfirstlane_b32 s7, v212
	s_lshl_b32 s7, s7, 14
	v_add_u32_e32 v249, s7, v249
	v_xor_b32_e32 v250, 64, v249
	s_add_i32 m0, s7, 0x0
	s_add_u32 s4, s8, 0x0
	s_addc_u32 s5, s9, 0
	global_load_lds_dwordx4 v248, s[4:5]
	s_add_i32 m0, s7, 0x400
	s_add_u32 s4, s8, 0x8000
	s_addc_u32 s5, s9, 0
	global_load_lds_dwordx4 v248, s[4:5]
	s_add_i32 m0, s7, 0x2000
	s_add_u32 s4, s10, 0x0
	s_addc_u32 s5, s11, 0
	global_load_lds_dwordx4 v248, s[4:5]
	s_add_i32 m0, s7, 0x2400
	s_add_u32 s4, s10, 0x8000
	s_addc_u32 s5, s11, 0
	global_load_lds_dwordx4 v248, s[4:5]
	s_add_i32 m0, s7, 0x800
	s_add_u32 s4, s8, 0x10000
	s_addc_u32 s5, s9, 0
	global_load_lds_dwordx4 v248, s[4:5]
	s_add_i32 m0, s7, 0xc00
	s_add_u32 s4, s8, 0x18000
	s_addc_u32 s5, s9, 0
	global_load_lds_dwordx4 v248, s[4:5]
	s_add_i32 m0, s7, 0x2800
	s_add_u32 s4, s10, 0x10000
	s_addc_u32 s5, s11, 0
	global_load_lds_dwordx4 v248, s[4:5]
	s_add_i32 m0, s7, 0x2c00
	s_add_u32 s4, s10, 0x18000
	s_addc_u32 s5, s11, 0
	global_load_lds_dwordx4 v248, s[4:5]
	s_add_i32 m0, s7, 0x1000
	s_add_u32 s4, s8, 0x20000
	s_addc_u32 s5, s9, 0
	global_load_lds_dwordx4 v248, s[4:5]
	s_add_i32 m0, s7, 0x1400
	s_add_u32 s4, s8, 0x28000
	s_addc_u32 s5, s9, 0
	global_load_lds_dwordx4 v248, s[4:5]
	s_add_i32 m0, s7, 0x3000
	s_add_u32 s4, s10, 0x20000
	s_addc_u32 s5, s11, 0
	global_load_lds_dwordx4 v248, s[4:5]
	s_add_i32 m0, s7, 0x3400
	s_add_u32 s4, s10, 0x28000
	s_addc_u32 s5, s11, 0
	global_load_lds_dwordx4 v248, s[4:5]
	s_add_i32 m0, s7, 0x1800
	s_add_u32 s4, s8, 0x30000
	s_addc_u32 s5, s9, 0
	global_load_lds_dwordx4 v248, s[4:5]
	s_add_i32 m0, s7, 0x1c00
	s_add_u32 s4, s8, 0x38000
	s_addc_u32 s5, s9, 0
	global_load_lds_dwordx4 v248, s[4:5]
	s_add_i32 m0, s7, 0x3800
	s_add_u32 s4, s10, 0x30000
	s_addc_u32 s5, s11, 0
	global_load_lds_dwordx4 v248, s[4:5]
	s_add_i32 m0, s7, 0x3c00
	s_add_u32 s4, s10, 0x38000
	s_addc_u32 s5, s11, 0
	global_load_lds_dwordx4 v248, s[4:5]
	s_waitcnt vmcnt(12)
	ds_read_b128 v[102:105], v249 offset:0
	ds_read_b128 v[106:109], v250 offset:0
	ds_read_b128 v[150:153], v249 offset:8192
	ds_read_b128 v[154:157], v250 offset:8192
	s_waitcnt lgkmcnt(0)
	s_add_i32 m0, s7, 0x0
	s_add_u32 s4, s8, 0x80
	s_addc_u32 s5, s9, 0
	global_load_lds_dwordx4 v248, s[4:5]
	s_add_i32 m0, s7, 0x400
	s_add_u32 s4, s8, 0x8080
	s_addc_u32 s5, s9, 0
	global_load_lds_dwordx4 v248, s[4:5]
	s_add_i32 m0, s7, 0x2000
	s_add_u32 s4, s10, 0x80
	s_addc_u32 s5, s11, 0
	global_load_lds_dwordx4 v248, s[4:5]
	s_add_i32 m0, s7, 0x2400
	s_add_u32 s4, s10, 0x8080
	s_addc_u32 s5, s11, 0
	global_load_lds_dwordx4 v248, s[4:5]
	v_mfma_f32_16x16x32_bf16 v[10:13], v[102:105], v[150:153], v[10:13]
	s_nop 7
	v_mfma_f32_16x16x32_bf16 v[10:13], v[106:109], v[154:157], v[10:13]
	s_waitcnt vmcnt(12)
; template <bool GATE>
; __device__ __forceinline__ void sample_gemm_res(LAS unsigned char* lds, const bf16* Amat, const bf16* Bt, const bf16* Hin, bf16* Hout, float* rss_out, const bf16* PP, const float* rss_in, int bid, int tid) {
;     ...
;     for (int ks = 0; ks < 8; ++ks) { bf16x8 a[4], b[4];
; #pragma unroll
;         for (int q = 0; q < 4; ++q) { a[q] = ap[(size_t)q * 16 * 256 + ks * 4]; b[q] = bp[(size_t)q * 16 * 256 + ks * 4]; }
; #pragma unroll
;         for (int mi = 0; mi < 4; ++mi)
; #pragma unroll
;             for (int ni = 0; ni < 4; ++ni) acc[mi][ni] = __builtin_amdgcn_mfma_f32_16x16x32_bf16(a[mi], b[ni], acc[mi][ni], 0, 0, 0); }
	ds_read_b128 v[110:113], v249 offset:2048
	ds_read_b128 v[114:117], v250 offset:2048
	ds_read_b128 v[158:161], v249 offset:10240
	ds_read_b128 v[162:165], v250 offset:10240
	s_waitcnt lgkmcnt(0)
	s_add_i32 m0, s7, 0x800
	s_add_u32 s4, s8, 0x10080
	s_addc_u32 s5, s9, 0
	global_load_lds_dwordx4 v248, s[4:5]
	s_add_i32 m0, s7, 0xc00
	s_add_u32 s4, s8, 0x18080
	s_addc_u32 s5, s9, 0
	global_load_lds_dwordx4 v248, s[4:5]
	s_add_i32 m0, s7, 0x2800
	s_add_u32 s4, s10, 0x10080
	s_addc_u32 s5, s11, 0
	global_load_lds_dwordx4 v248, s[4:5]
	s_add_i32 m0, s7, 0x2c00
	s_add_u32 s4, s10, 0x18080
	s_addc_u32 s5, s11, 0
	global_load_lds_dwordx4 v248, s[4:5]
	v_mfma_f32_16x16x32_bf16 v[26:29], v[110:113], v[150:153], v[26:29]
	v_mfma_f32_16x16x32_bf16 v[14:17], v[102:105], v[158:161], v[14:17]
	v_mfma_f32_16x16x32_bf16 v[34:37], v[110:113], v[158:161], v[34:37]
	v_mfma_f32_16x16x32_bf16 v[26:29], v[114:117], v[154:157], v[26:29]
	v_mfma_f32_16x16x32_bf16 v[14:17], v[106:109], v[162:165], v[14:17]
	v_mfma_f32_16x16x32_bf16 v[34:37], v[114:117], v[162:165], v[34:37]
	s_waitcnt vmcnt(12)
	ds_read_b128 v[118:121], v249 offset:4096
	ds_read_b128 v[122:125], v250 offset:4096
	ds_read_b128 v[166:169], v249 offset:12288
	ds_read_b128 v[170:173], v250 offset:12288
	s_waitcnt lgkmcnt(0)
	s_add_i32 m0, s7, 0x1000
	s_add_u32 s4, s8, 0x20080
	s_addc_u32 s5, s9, 0
	global_load_lds_dwordx4 v248, s[4:5]
	s_add_i32 m0, s7, 0x1400
	s_add_u32 s4, s8, 0x28080
	s_addc_u32 s5, s9, 0
	global_load_lds_dwordx4 v248, s[4:5]
	s_add_i32 m0, s7, 0x3000
	s_add_u32 s4, s10, 0x20080
	s_addc_u32 s5, s11, 0
	global_load_lds_dwordx4 v248, s[4:5]
	s_add_i32 m0, s7, 0x3400
	s_add_u32 s4, s10, 0x28080
	s_addc_u32 s5, s11, 0
	global_load_lds_dwordx4 v248, s[4:5]
	v_mfma_f32_16x16x32_bf16 v[42:45], v[118:121], v[150:153], v[42:45]
	v_mfma_f32_16x16x32_bf16 v[50:53], v[118:121], v[158:161], v[50:53]
	v_mfma_f32_16x16x32_bf16 v[18:21], v[102:105], v[166:169], v[18:21]
	v_mfma_f32_16x16x32_bf16 v[30:33], v[110:113], v[166:169], v[30:33]
	v_mfma_f32_16x16x32_bf16 v[46:49], v[118:121], v[166:169], v[46:49]
	v_mfma_f32_16x16x32_bf16 v[42:45], v[122:125], v[154:157], v[42:45]
	v_mfma_f32_16x16x32_bf16 v[50:53], v[122:125], v[162:165], v[50:53]
	v_mfma_f32_16x16x32_bf16 v[18:21], v[106:109], v[170:173], v[18:21]
	v_mfma_f32_16x16x32_bf16 v[30:33], v[114:117], v[170:173], v[30:33]
	v_mfma_f32_16x16x32_bf16 v[46:49], v[122:125], v[170:173], v[46:49]
	s_waitcnt vmcnt(12)
	ds_read_b128 v[126:129], v249 offset:6144
	ds_read_b128 v[130:133], v250 offset:6144
	ds_read_b128 v[174:177], v249 offset:14336
	ds_read_b128 v[178:181], v250 offset:14336
	s_waitcnt lgkmcnt(0)
	s_add_i32 m0, s7, 0x1800
	s_add_u32 s4, s8, 0x30080
	s_addc_u32 s5, s9, 0
	global_load_lds_dwordx4 v248, s[4:5]
	s_add_i32 m0, s7, 0x1c00
	s_add_u32 s4, s8, 0x38080
	s_addc_u32 s5, s9, 0
	global_load_lds_dwordx4 v248, s[4:5]
	s_add_i32 m0, s7, 0x3800
	s_add_u32 s4, s10, 0x30080
	s_addc_u32 s5, s11, 0
	global_load_lds_dwordx4 v248, s[4:5]
	s_add_i32 m0, s7, 0x3c00
	s_add_u32 s4, s10, 0x38080
	s_addc_u32 s5, s11, 0
	global_load_lds_dwordx4 v248, s[4:5]
	v_mfma_f32_16x16x32_bf16 v[54:57], v[126:129], v[150:153], v[54:57]
	v_mfma_f32_16x16x32_bf16 v[66:69], v[126:129], v[158:161], v[66:69]
	v_mfma_f32_16x16x32_bf16 v[62:65], v[126:129], v[166:169], v[62:65]
	v_mfma_f32_16x16x32_bf16 v[22:25], v[102:105], v[174:177], v[22:25]
	v_mfma_f32_16x16x32_bf16 v[38:41], v[110:113], v[174:177], v[38:41]
	v_mfma_f32_16x16x32_bf16 v[58:61], v[118:121], v[174:177], v[58:61]
	v_mfma_f32_16x16x32_bf16 v[70:73], v[126:129], v[174:177], v[70:73]
	v_mfma_f32_16x16x32_bf16 v[54:57], v[130:133], v[154:157], v[54:57]
	v_mfma_f32_16x16x32_bf16 v[66:69], v[130:133], v[162:165], v[66:69]
	v_mfma_f32_16x16x32_bf16 v[62:65], v[130:133], v[170:173], v[62:65]
	v_mfma_f32_16x16x32_bf16 v[22:25], v[106:109], v[178:181], v[22:25]
	v_mfma_f32_16x16x32_bf16 v[38:41], v[114:117], v[178:181], v[38:41]
	v_mfma_f32_16x16x32_bf16 v[58:61], v[122:125], v[178:181], v[58:61]
	v_mfma_f32_16x16x32_bf16 v[70:73], v[130:133], v[178:181], v[70:73]
	s_waitcnt vmcnt(12)
	ds_read_b128 v[102:105], v249 offset:0
	ds_read_b128 v[106:109], v250 offset:0
	ds_read_b128 v[150:153], v249 offset:8192
	ds_read_b128 v[154:157], v250 offset:8192
	s_waitcnt lgkmcnt(0)
	s_add_i32 m0, s7, 0x0
	s_add_u32 s4, s8, 0x100
	s_addc_u32 s5, s9, 0
	global_load_lds_dwordx4 v248, s[4:5]
	s_add_i32 m0, s7, 0x400
	s_add_u32 s4, s8, 0x8100
	s_addc_u32 s5, s9, 0
	global_load_lds_dwordx4 v248, s[4:5]
	s_add_i32 m0, s7, 0x2000
	s_add_u32 s4, s10, 0x100
	s_addc_u32 s5, s11, 0
	global_load_lds_dwordx4 v248, s[4:5]
	s_add_i32 m0, s7, 0x2400
	s_add_u32 s4, s10, 0x8100
	s_addc_u32 s5, s11, 0
	global_load_lds_dwordx4 v248, s[4:5]
	v_mfma_f32_16x16x32_bf16 v[10:13], v[102:105], v[150:153], v[10:13]
	s_nop 7
	v_mfma_f32_16x16x32_bf16 v[10:13], v[106:109], v[154:157], v[10:13]
	s_waitcnt vmcnt(12)
	ds_read_b128 v[110:113], v249 offset:2048
	ds_read_b128 v[114:117], v250 offset:2048
	ds_read_b128 v[158:161], v249 offset:10240
	ds_read_b128 v[162:165], v250 offset:10240
	s_waitcnt lgkmcnt(0)
	s_add_i32 m0, s7, 0x800
	s_add_u32 s4, s8, 0x10100
	s_addc_u32 s5, s9, 0
	global_load_lds_dwordx4 v248, s[4:5]
	s_add_i32 m0, s7, 0xc00
	s_add_u32 s4, s8, 0x18100
	s_addc_u32 s5, s9, 0
	global_load_lds_dwordx4 v248, s[4:5]
	s_add_i32 m0, s7, 0x2800
	s_add_u32 s4, s10, 0x10100
	s_addc_u32 s5, s11, 0
	global_load_lds_dwordx4 v248, s[4:5]
	s_add_i32 m0, s7, 0x2c00
	s_add_u32 s4, s10, 0x18100
	s_addc_u32 s5, s11, 0
	global_load_lds_dwordx4 v248, s[4:5]
	v_mfma_f32_16x16x32_bf16 v[26:29], v[110:113], v[150:153], v[26:29]
	v_mfma_f32_16x16x32_bf16 v[14:17], v[102:105], v[158:161], v[14:17]
	v_mfma_f32_16x16x32_bf16 v[34:37], v[110:113], v[158:161], v[34:37]
	v_mfma_f32_16x16x32_bf16 v[26:29], v[114:117], v[154:157], v[26:29]
	v_mfma_f32_16x16x32_bf16 v[14:17], v[106:109], v[162:165], v[14:17]
	v_mfma_f32_16x16x32_bf16 v[34:37], v[114:117], v[162:165], v[34:37]
	s_waitcnt vmcnt(12)
; template <bool GATE>
; __device__ __forceinline__ void sample_gemm_res(LAS unsigned char* lds, const bf16* Amat, const bf16* Bt, const bf16* Hin, bf16* Hout, float* rss_out, const bf16* PP, const float* rss_in, int bid, int tid) {
;     ...
;     for (int ks = 0; ks < 8; ++ks) { bf16x8 a[4], b[4];
; #pragma unroll
;         for (int q = 0; q < 4; ++q) { a[q] = ap[(size_t)q * 16 * 256 + ks * 4]; b[q] = bp[(size_t)q * 16 * 256 + ks * 4]; }
; #pragma unroll
;         for (int mi = 0; mi < 4; ++mi)
; #pragma unroll
;             for (int ni = 0; ni < 4; ++ni) acc[mi][ni] = __builtin_amdgcn_mfma_f32_16x16x32_bf16(a[mi], b[ni], acc[mi][ni], 0, 0, 0); }
	ds_read_b128 v[118:121], v249 offset:4096
	ds_read_b128 v[122:125], v250 offset:4096
	ds_read_b128 v[166:169], v249 offset:12288
	ds_read_b128 v[170:173], v250 offset:12288
	s_waitcnt lgkmcnt(0)
	s_add_i32 m0, s7, 0x1000
	s_add_u32 s4, s8, 0x20100
	s_addc_u32 s5, s9, 0
	global_load_lds_dwordx4 v248, s[4:5]
	s_add_i32 m0, s7, 0x1400
	s_add_u32 s4, s8, 0x28100
	s_addc_u32 s5, s9, 0
	global_load_lds_dwordx4 v248, s[4:5]
	s_add_i32 m0, s7, 0x3000
	s_add_u32 s4, s10, 0x20100
	s_addc_u32 s5, s11, 0
	global_load_lds_dwordx4 v248, s[4:5]
	s_add_i32 m0, s7, 0x3400
	s_add_u32 s4, s10, 0x28100
	s_addc_u32 s5, s11, 0
	global_load_lds_dwordx4 v248, s[4:5]
	v_mfma_f32_16x16x32_bf16 v[42:45], v[118:121], v[150:153], v[42:45]
	v_mfma_f32_16x16x32_bf16 v[50:53], v[118:121], v[158:161], v[50:53]
	v_mfma_f32_16x16x32_bf16 v[18:21], v[102:105], v[166:169], v[18:21]
	v_mfma_f32_16x16x32_bf16 v[30:33], v[110:113], v[166:169], v[30:33]
	v_mfma_f32_16x16x32_bf16 v[46:49], v[118:121], v[166:169], v[46:49]
	v_mfma_f32_16x16x32_bf16 v[42:45], v[122:125], v[154:157], v[42:45]
	v_mfma_f32_16x16x32_bf16 v[50:53], v[122:125], v[162:165], v[50:53]
	v_mfma_f32_16x16x32_bf16 v[18:21], v[106:109], v[170:173], v[18:21]
	v_mfma_f32_16x16x32_bf16 v[30:33], v[114:117], v[170:173], v[30:33]
	v_mfma_f32_16x16x32_bf16 v[46:49], v[122:125], v[170:173], v[46:49]
	s_waitcnt vmcnt(12)
	ds_read_b128 v[126:129], v249 offset:6144
	ds_read_b128 v[130:133], v250 offset:6144
	ds_read_b128 v[174:177], v249 offset:14336
	ds_read_b128 v[178:181], v250 offset:14336
	s_waitcnt lgkmcnt(0)
	s_add_i32 m0, s7, 0x1800
	s_add_u32 s4, s8, 0x30100
	s_addc_u32 s5, s9, 0
	global_load_lds_dwordx4 v248, s[4:5]
	s_add_i32 m0, s7, 0x1c00
	s_add_u32 s4, s8, 0x38100
	s_addc_u32 s5, s9, 0
	global_load_lds_dwordx4 v248, s[4:5]
	s_add_i32 m0, s7, 0x3800
	s_add_u32 s4, s10, 0x30100
	s_addc_u32 s5, s11, 0
	global_load_lds_dwordx4 v248, s[4:5]
	s_add_i32 m0, s7, 0x3c00
	s_add_u32 s4, s10, 0x38100
	s_addc_u32 s5, s11, 0
	global_load_lds_dwordx4 v248, s[4:5]
	v_mfma_f32_16x16x32_bf16 v[54:57], v[126:129], v[150:153], v[54:57]
	v_mfma_f32_16x16x32_bf16 v[66:69], v[126:129], v[158:161], v[66:69]
	v_mfma_f32_16x16x32_bf16 v[62:65], v[126:129], v[166:169], v[62:65]
	v_mfma_f32_16x16x32_bf16 v[22:25], v[102:105], v[174:177], v[22:25]
	v_mfma_f32_16x16x32_bf16 v[38:41], v[110:113], v[174:177], v[38:41]
	v_mfma_f32_16x16x32_bf16 v[58:61], v[118:121], v[174:177], v[58:61]
	v_mfma_f32_16x16x32_bf16 v[70:73], v[126:129], v[174:177], v[70:73]
	v_mfma_f32_16x16x32_bf16 v[54:57], v[130:133], v[154:157], v[54:57]
	v_mfma_f32_16x16x32_bf16 v[66:69], v[130:133], v[162:165], v[66:69]
	v_mfma_f32_16x16x32_bf16 v[62:65], v[130:133], v[170:173], v[62:65]
	v_mfma_f32_16x16x32_bf16 v[22:25], v[106:109], v[178:181], v[22:25]
	v_mfma_f32_16x16x32_bf16 v[38:41], v[114:117], v[178:181], v[38:41]
	v_mfma_f32_16x16x32_bf16 v[58:61], v[122:125], v[178:181], v[58:61]
	v_mfma_f32_16x16x32_bf16 v[70:73], v[130:133], v[178:181], v[70:73]
	s_waitcnt vmcnt(12)
	ds_read_b128 v[102:105], v249 offset:0
	ds_read_b128 v[106:109], v250 offset:0
	ds_read_b128 v[150:153], v249 offset:8192
	ds_read_b128 v[154:157], v250 offset:8192
	s_waitcnt lgkmcnt(0)
	s_add_i32 m0, s7, 0x0
	s_add_u32 s4, s8, 0x180
	s_addc_u32 s5, s9, 0
	global_load_lds_dwordx4 v248, s[4:5]
	s_add_i32 m0, s7, 0x400
	s_add_u32 s4, s8, 0x8180
	s_addc_u32 s5, s9, 0
	global_load_lds_dwordx4 v248, s[4:5]
	s_add_i32 m0, s7, 0x2000
	s_add_u32 s4, s10, 0x180
	s_addc_u32 s5, s11, 0
	global_load_lds_dwordx4 v248, s[4:5]
	s_add_i32 m0, s7, 0x2400
	s_add_u32 s4, s10, 0x8180
	s_addc_u32 s5, s11, 0
	global_load_lds_dwordx4 v248, s[4:5]
	v_mfma_f32_16x16x32_bf16 v[10:13], v[102:105], v[150:153], v[10:13]
	s_nop 7
	v_mfma_f32_16x16x32_bf16 v[10:13], v[106:109], v[154:157], v[10:13]
	s_waitcnt vmcnt(12)
	ds_read_b128 v[110:113], v249 offset:2048
	ds_read_b128 v[114:117], v250 offset:2048
	ds_read_b128 v[158:161], v249 offset:10240
	ds_read_b128 v[162:165], v250 offset:10240
	s_waitcnt lgkmcnt(0)
	s_add_i32 m0, s7, 0x800
	s_add_u32 s4, s8, 0x10180
	s_addc_u32 s5, s9, 0
	global_load_lds_dwordx4 v248, s[4:5]
	s_add_i32 m0, s7, 0xc00
	s_add_u32 s4, s8, 0x18180
	s_addc_u32 s5, s9, 0
	global_load_lds_dwordx4 v248, s[4:5]
	s_add_i32 m0, s7, 0x2800
	s_add_u32 s4, s10, 0x10180
	s_addc_u32 s5, s11, 0
	global_load_lds_dwordx4 v248, s[4:5]
	s_add_i32 m0, s7, 0x2c00
	s_add_u32 s4, s10, 0x18180
	s_addc_u32 s5, s11, 0
	global_load_lds_dwordx4 v248, s[4:5]
	v_mfma_f32_16x16x32_bf16 v[26:29], v[110:113], v[150:153], v[26:29]
	v_mfma_f32_16x16x32_bf16 v[14:17], v[102:105], v[158:161], v[14:17]
	v_mfma_f32_16x16x32_bf16 v[34:37], v[110:113], v[158:161], v[34:37]
	v_mfma_f32_16x16x32_bf16 v[26:29], v[114:117], v[154:157], v[26:29]
	v_mfma_f32_16x16x32_bf16 v[14:17], v[106:109], v[162:165], v[14:17]
	v_mfma_f32_16x16x32_bf16 v[34:37], v[114:117], v[162:165], v[34:37]
	s_waitcnt vmcnt(12)
	ds_read_b128 v[118:121], v249 offset:4096
	ds_read_b128 v[122:125], v250 offset:4096
	ds_read_b128 v[166:169], v249 offset:12288
	ds_read_b128 v[170:173], v250 offset:12288
	s_waitcnt lgkmcnt(0)
; #define LAS __attribute__((address_space(3)))
; template <bool GATE>
; __device__ __forceinline__ void sample_gemm_res(LAS unsigned char* lds, const bf16* Amat, const bf16* Bt, const bf16* Hin, bf16* Hout, float* rss_out, const bf16* PP, const float* rss_in, int bid, int tid) {
;     ...
;     for (int ks = 0; ks < 8; ++ks) { bf16x8 a[4], b[4];
; #pragma unroll
;         for (int q = 0; q < 4; ++q) { a[q] = ap[(size_t)q * 16 * 256 + ks * 4]; b[q] = bp[(size_t)q * 16 * 256 + ks * 4]; }
; #pragma unroll
;         for (int mi = 0; mi < 4; ++mi)
; #pragma unroll
;             for (int ni = 0; ni < 4; ++ni) acc[mi][ni] = __builtin_amdgcn_mfma_f32_16x16x32_bf16(a[mi], b[ni], acc[mi][ni], 0, 0, 0); }
;     LAS float* red = (LAS float*)lds;
;     __syncthreads();
	s_add_i32 m0, s7, 0x1000
	s_add_u32 s4, s8, 0x20180
	s_addc_u32 s5, s9, 0
	global_load_lds_dwordx4 v248, s[4:5]
	s_add_i32 m0, s7, 0x1400
	s_add_u32 s4, s8, 0x28180
	s_addc_u32 s5, s9, 0
	global_load_lds_dwordx4 v248, s[4:5]
	s_add_i32 m0, s7, 0x3000
	s_add_u32 s4, s10, 0x20180
	s_addc_u32 s5, s11, 0
	global_load_lds_dwordx4 v248, s[4:5]
	s_add_i32 m0, s7, 0x3400
	s_add_u32 s4, s10, 0x28180
	s_addc_u32 s5, s11, 0
	global_load_lds_dwordx4 v248, s[4:5]
	v_mfma_f32_16x16x32_bf16 v[42:45], v[118:121], v[150:153], v[42:45]
	v_mfma_f32_16x16x32_bf16 v[50:53], v[118:121], v[158:161], v[50:53]
	v_mfma_f32_16x16x32_bf16 v[18:21], v[102:105], v[166:169], v[18:21]
	v_mfma_f32_16x16x32_bf16 v[30:33], v[110:113], v[166:169], v[30:33]
	v_mfma_f32_16x16x32_bf16 v[46:49], v[118:121], v[166:169], v[46:49]
	v_mfma_f32_16x16x32_bf16 v[42:45], v[122:125], v[154:157], v[42:45]
	v_mfma_f32_16x16x32_bf16 v[50:53], v[122:125], v[162:165], v[50:53]
	v_mfma_f32_16x16x32_bf16 v[18:21], v[106:109], v[170:173], v[18:21]
	v_mfma_f32_16x16x32_bf16 v[30:33], v[114:117], v[170:173], v[30:33]
	v_mfma_f32_16x16x32_bf16 v[46:49], v[122:125], v[170:173], v[46:49]
	s_waitcnt vmcnt(12)
	ds_read_b128 v[126:129], v249 offset:6144
	ds_read_b128 v[130:133], v250 offset:6144
	ds_read_b128 v[174:177], v249 offset:14336
	ds_read_b128 v[178:181], v250 offset:14336
	s_waitcnt lgkmcnt(0)
	s_add_i32 m0, s7, 0x1800
	s_add_u32 s4, s8, 0x30180
	s_addc_u32 s5, s9, 0
	global_load_lds_dwordx4 v248, s[4:5]
	s_add_i32 m0, s7, 0x1c00
	s_add_u32 s4, s8, 0x38180
	s_addc_u32 s5, s9, 0
	global_load_lds_dwordx4 v248, s[4:5]
	s_add_i32 m0, s7, 0x3800
	s_add_u32 s4, s10, 0x30180
	s_addc_u32 s5, s11, 0
	global_load_lds_dwordx4 v248, s[4:5]
	s_add_i32 m0, s7, 0x3c00
	s_add_u32 s4, s10, 0x38180
	s_addc_u32 s5, s11, 0
	global_load_lds_dwordx4 v248, s[4:5]
	v_mfma_f32_16x16x32_bf16 v[54:57], v[126:129], v[150:153], v[54:57]
	v_mfma_f32_16x16x32_bf16 v[66:69], v[126:129], v[158:161], v[66:69]
	v_mfma_f32_16x16x32_bf16 v[62:65], v[126:129], v[166:169], v[62:65]
	v_mfma_f32_16x16x32_bf16 v[22:25], v[102:105], v[174:177], v[22:25]
	v_mfma_f32_16x16x32_bf16 v[38:41], v[110:113], v[174:177], v[38:41]
	v_mfma_f32_16x16x32_bf16 v[58:61], v[118:121], v[174:177], v[58:61]
	v_mfma_f32_16x16x32_bf16 v[70:73], v[126:129], v[174:177], v[70:73]
	v_mfma_f32_16x16x32_bf16 v[54:57], v[130:133], v[154:157], v[54:57]
	v_mfma_f32_16x16x32_bf16 v[66:69], v[130:133], v[162:165], v[66:69]
	v_mfma_f32_16x16x32_bf16 v[62:65], v[130:133], v[170:173], v[62:65]
	v_mfma_f32_16x16x32_bf16 v[22:25], v[106:109], v[178:181], v[22:25]
	v_mfma_f32_16x16x32_bf16 v[38:41], v[114:117], v[178:181], v[38:41]
	v_mfma_f32_16x16x32_bf16 v[58:61], v[122:125], v[178:181], v[58:61]
	v_mfma_f32_16x16x32_bf16 v[70:73], v[130:133], v[178:181], v[70:73]
	s_waitcnt vmcnt(12)
	ds_read_b128 v[102:105], v249 offset:0
	ds_read_b128 v[106:109], v250 offset:0
	ds_read_b128 v[150:153], v249 offset:8192
	ds_read_b128 v[154:157], v250 offset:8192
	s_waitcnt lgkmcnt(0)
	v_mfma_f32_16x16x32_bf16 v[10:13], v[102:105], v[150:153], v[10:13]
	s_nop 7
	v_mfma_f32_16x16x32_bf16 v[10:13], v[106:109], v[154:157], v[10:13]
	s_waitcnt vmcnt(8)
	ds_read_b128 v[110:113], v249 offset:2048
	ds_read_b128 v[114:117], v250 offset:2048
	ds_read_b128 v[158:161], v249 offset:10240
	ds_read_b128 v[162:165], v250 offset:10240
	s_waitcnt lgkmcnt(0)
	v_mfma_f32_16x16x32_bf16 v[26:29], v[110:113], v[150:153], v[26:29]
	v_mfma_f32_16x16x32_bf16 v[14:17], v[102:105], v[158:161], v[14:17]
	v_mfma_f32_16x16x32_bf16 v[34:37], v[110:113], v[158:161], v[34:37]
	v_mfma_f32_16x16x32_bf16 v[26:29], v[114:117], v[154:157], v[26:29]
	v_mfma_f32_16x16x32_bf16 v[14:17], v[106:109], v[162:165], v[14:17]
	v_mfma_f32_16x16x32_bf16 v[34:37], v[114:117], v[162:165], v[34:37]
	s_waitcnt vmcnt(4)
	ds_read_b128 v[118:121], v249 offset:4096
	ds_read_b128 v[122:125], v250 offset:4096
	ds_read_b128 v[166:169], v249 offset:12288
	ds_read_b128 v[170:173], v250 offset:12288
	s_waitcnt lgkmcnt(0)
	v_mfma_f32_16x16x32_bf16 v[42:45], v[118:121], v[150:153], v[42:45]
	v_mfma_f32_16x16x32_bf16 v[50:53], v[118:121], v[158:161], v[50:53]
	v_mfma_f32_16x16x32_bf16 v[18:21], v[102:105], v[166:169], v[18:21]
	v_mfma_f32_16x16x32_bf16 v[30:33], v[110:113], v[166:169], v[30:33]
	v_mfma_f32_16x16x32_bf16 v[46:49], v[118:121], v[166:169], v[46:49]
	v_mfma_f32_16x16x32_bf16 v[42:45], v[122:125], v[154:157], v[42:45]
	v_mfma_f32_16x16x32_bf16 v[50:53], v[122:125], v[162:165], v[50:53]
	v_mfma_f32_16x16x32_bf16 v[18:21], v[106:109], v[170:173], v[18:21]
	v_mfma_f32_16x16x32_bf16 v[30:33], v[114:117], v[170:173], v[30:33]
	v_mfma_f32_16x16x32_bf16 v[46:49], v[122:125], v[170:173], v[46:49]
	s_waitcnt vmcnt(0)
	ds_read_b128 v[126:129], v249 offset:6144
	ds_read_b128 v[130:133], v250 offset:6144
	ds_read_b128 v[174:177], v249 offset:14336
	ds_read_b128 v[178:181], v250 offset:14336
	s_waitcnt lgkmcnt(0)
	v_mfma_f32_16x16x32_bf16 v[54:57], v[126:129], v[150:153], v[54:57]
	v_mfma_f32_16x16x32_bf16 v[66:69], v[126:129], v[158:161], v[66:69]
	v_mfma_f32_16x16x32_bf16 v[62:65], v[126:129], v[166:169], v[62:65]
	v_mfma_f32_16x16x32_bf16 v[22:25], v[102:105], v[174:177], v[22:25]
	v_mfma_f32_16x16x32_bf16 v[38:41], v[110:113], v[174:177], v[38:41]
	v_mfma_f32_16x16x32_bf16 v[58:61], v[118:121], v[174:177], v[58:61]
	v_mfma_f32_16x16x32_bf16 v[70:73], v[126:129], v[174:177], v[70:73]
	v_mfma_f32_16x16x32_bf16 v[54:57], v[130:133], v[154:157], v[54:57]
	v_mfma_f32_16x16x32_bf16 v[66:69], v[130:133], v[162:165], v[66:69]
	v_mfma_f32_16x16x32_bf16 v[62:65], v[130:133], v[170:173], v[62:65]
	v_mfma_f32_16x16x32_bf16 v[22:25], v[106:109], v[178:181], v[22:25]
	v_mfma_f32_16x16x32_bf16 v[38:41], v[114:117], v[178:181], v[38:41]
	v_mfma_f32_16x16x32_bf16 v[58:61], v[122:125], v[178:181], v[58:61]
	v_mfma_f32_16x16x32_bf16 v[70:73], v[130:133], v[178:181], v[70:73]
	s_nop 7
	s_nop 7
	v_add_u32_e32 v0, 0x1000, v93
	s_barrier
; #define LAS __attribute__((address_space(3)))
; template <bool GATE>
; __device__ __forceinline__ void sample_gemm_res(LAS unsigned char* lds, const bf16* Amat, const bf16* Bt, const bf16* Hin, bf16* Hout, float* rss_out, const bf16* PP, const float* rss_in, int bid, int tid) {
;     ...
;     LAS float* red = (LAS float*)lds;
;     __syncthreads();
; #pragma unroll
;     for (int mi = 0; mi < 4; ++mi)
; #pragma unroll
;         for (int ni = 0; ni < 4; ++ni)
; #pragma unroll
;             for (int i = 0; i < 4; ++i) red[(wave * 64 + 16 * mi + kg * 4 + i) * 65 + 16 * ni + lr] = acc[mi][ni][i];
;     __syncthreads();
	ds_write2_b32 v93, v10, v14 offset1:16
	ds_write2_b32 v93, v11, v15 offset0:65 offset1:81
	ds_write2_b32 v93, v12, v16 offset0:130 offset1:146
	ds_write2_b32 v93, v13, v17 offset0:195 offset1:211
	ds_write2_b32 v93, v18, v22 offset0:32 offset1:48
	ds_write2_b32 v93, v19, v23 offset0:97 offset1:113
	ds_write2_b32 v93, v20, v24 offset0:162 offset1:178
	ds_write2_b32 v93, v21, v25 offset0:227 offset1:243
	ds_write2_b32 v0, v26, v34 offset0:16 offset1:32
	ds_write2_b32 v0, v27, v35 offset0:81 offset1:97
	ds_write2_b32 v0, v28, v36 offset0:146 offset1:162
	ds_write2_b32 v0, v29, v37 offset0:211 offset1:227
	ds_write2_b32 v0, v30, v38 offset0:48 offset1:64
	ds_write2_b32 v0, v31, v39 offset0:113 offset1:129
	ds_write2_b32 v0, v32, v40 offset0:178 offset1:194
	v_add_u32_e32 v0, 0x1200, v93
	ds_write2_b32 v0, v33, v41 offset0:115 offset1:131
	v_add_u32_e32 v0, 0x2000, v93
	ds_write2_b32 v0, v42, v50 offset0:32 offset1:48
	ds_write2_b32 v0, v43, v51 offset0:97 offset1:113
	ds_write2_b32 v0, v44, v52 offset0:162 offset1:178
	ds_write2_b32 v0, v45, v53 offset0:227 offset1:243
	ds_write2_b32 v0, v46, v58 offset0:64 offset1:80
	ds_write2_b32 v0, v47, v59 offset0:129 offset1:145
	ds_write2_b32 v0, v48, v60 offset0:194 offset1:210
	v_add_u32_e32 v0, 0x2400, v93
	ds_write2_b32 v0, v49, v61 offset0:3 offset1:19
	v_add_u32_e32 v0, 0x3000, v93
	v_add_u32_e32 v10, 0x3200, v93
	ds_write2_b32 v0, v54, v66 offset0:48 offset1:64
	ds_write2_b32 v0, v55, v67 offset0:113 offset1:129
	ds_write2_b32 v0, v56, v68 offset0:178 offset1:194
	ds_write2_b32 v10, v57, v69 offset0:115 offset1:131
	ds_write2_b32 v0, v62, v70 offset0:80 offset1:96
	ds_write2_b32 v0, v63, v71 offset0:145 offset1:161
	ds_write2_b32 v0, v64, v72 offset0:210 offset1:226
	v_add_u32_e32 v0, 0x3400, v93
	ds_write2_b32 v0, v65, v73 offset0:19 offset1:35
	v_add_u32_e32 v0, v89, v94
	s_waitcnt lgkmcnt(0)
	s_barrier
; __device__ __forceinline__ unsigned cvtpk(float lo, float hi) { f32x2_t v = {lo, hi}; bf16x2_t b = __builtin_convertvector(v, bf16x2_t); return __builtin_bit_cast(unsigned, b); }
; template <bool GATE>
; __device__ __forceinline__ void sample_gemm_res(LAS unsigned char* lds, const bf16* Amat, const bf16* Bt, const bf16* Hin, bf16* Hout, float* rss_out, const bf16* PP, const float* rss_in, int bid, int tid) {
;     ...
;     { const int row = tid >> 3, c8 = (tid & 7) * 8, grow = m0 + row; float v[8];
; #pragma unroll
;       for (int e = 0; e < 8; ++e) { float sacc = 0.f;
; #pragma unroll
;           for (int w = 0; w < 8; ++w) sacc += red[(w * 64 + row) * 65 + c8 + e];
;           v[e] = sacc; }
;       float sc = 1.f; if (GATE) sc = rsqrtf(rsi * (1.f / 2048.f) + 1e-6f);
;       const size_t p = (size_t)grow * 2048 + n0 + c8;
;       const unsigned hws[4] = {hw.x, hw.y, hw.z, hw.w}, pws[4] = {pw.x, pw.y, pw.z, pw.w}; unsigned ow[4]; float sq = 0.f;
; #pragma unroll
;       for (int e2 = 0; e2 < 4; ++e2) { float h0 = __uint_as_float(hws[e2] << 16), h1 = __uint_as_float(hws[e2] & 0xffff0000u);
;           if (GATE) { h0 += __builtin_amdgcn_rcpf(1.f + __expf(-sc * v[2 * e2])) * __uint_as_float(pws[e2] << 16); h1 += __builtin_amdgcn_rcpf(1.f + __expf(-sc * v[2 * e2 + 1])) * __uint_as_float(pws[e2] & 0xffff0000u); }
;           else { h0 += v[2 * e2]; h1 += v[2 * e2 + 1]; }
;           sq += h0 * h0 + h1 * h1; ow[e2] = cvtpk(h0, h1); }
;       *(u32x4*)(Hout + p) = (u32x4){ow[0], ow[1], ow[2], ow[3]};
;       sq += __shfl_xor(sq, 1); sq += __shfl_xor(sq, 2); sq += __shfl_xor(sq, 4);
;       if ((tid & 7) == 0) atomicAdd(rss_out + grow, sq); }
;     __syncthreads();
;   }
	ds_read2_b32 v[10:11], v0 offset1:1
	v_add_u32_e32 v12, 0x4100, v0
	v_add_u32_e32 v14, 0x8200, v0
	v_add_u32_e32 v16, 0xc300, v0
	ds_read2_b32 v[12:13], v12 offset1:1
	ds_read2_b32 v[14:15], v14 offset1:1
	ds_read2_b32 v[16:17], v16 offset1:1
	ds_read2_b32 v[18:19], v0 offset0:2 offset1:3
	ds_read2_b32 v[20:21], v0 offset0:4 offset1:5
	ds_read2_b32 v[22:23], v0 offset0:6 offset1:7
	ds_read2_b32 v[24:25], v96 offset1:1
	ds_read2_b32 v[26:27], v97 offset1:1
	s_waitcnt lgkmcnt(8)
	v_add_f32_e32 v10, 0, v10
	s_waitcnt lgkmcnt(7)
	v_add_f32_e32 v10, v10, v12
	s_waitcnt lgkmcnt(6)
	v_add_f32_e32 v10, v10, v14
	s_waitcnt lgkmcnt(5)
	v_add_f32_e32 v10, v10, v16
	s_waitcnt lgkmcnt(1)
	v_add_f32_e32 v10, v10, v24
	ds_read2_b32 v[28:29], v96 offset0:2 offset1:3
	ds_read2_b32 v[30:31], v96 offset0:4 offset1:5
	ds_read2_b32 v[32:33], v96 offset0:6 offset1:7
	s_waitcnt lgkmcnt(3)
	v_add_f32_e32 v10, v10, v26
	ds_read2_b32 v[34:35], v98 offset1:1
	ds_read2_b32 v[36:37], v99 offset1:1
	ds_read2_b32 v[38:39], v97 offset0:2 offset1:3
	ds_read2_b32 v[40:41], v97 offset0:4 offset1:5
	ds_read2_b32 v[42:43], v97 offset0:6 offset1:7
	s_waitcnt lgkmcnt(4)
	v_add_f32_e32 v10, v10, v34
	s_waitcnt lgkmcnt(3)
	v_add_f32_e32 v50, v10, v36
	v_add_f32_e32 v10, 0, v11
	v_add_f32_e32 v10, v10, v13
	v_add_f32_e32 v10, v10, v15
	v_add_f32_e32 v10, v10, v17
	v_add_f32_e32 v10, v10, v25
	v_add_f32_e32 v10, v10, v27
	v_add_f32_e32 v10, v10, v35
	v_add_f32_e32 v51, v10, v37
	v_add_u32_e32 v10, 0x4108, v0
	ds_read2_b32 v[44:45], v98 offset0:2 offset1:3
	ds_read2_b32 v[46:47], v98 offset0:4 offset1:5
	ds_read2_b32 v[48:49], v98 offset0:6 offset1:7
	ds_read2_b32 v[10:11], v10 offset1:1
	v_add_f32_e32 v18, 0, v18
	v_add_u32_e32 v26, 0xc308, v0
	ds_read2_b32 v[12:13], v99 offset0:2 offset1:3
	ds_read2_b32 v[14:15], v99 offset0:4 offset1:5
	ds_read2_b32 v[16:17], v99 offset0:6 offset1:7
	v_add_u32_e32 v36, 0x8210, v0
	s_waitcnt lgkmcnt(3)
	v_add_f32_e32 v10, v18, v10
	v_add_u32_e32 v18, 0x8208, v0
	ds_read2_b32 v[24:25], v18 offset1:1
	ds_read2_b32 v[26:27], v26 offset1:1
	v_add_u32_e32 v18, 0x4110, v0
	ds_read2_b32 v[34:35], v18 offset1:1
	ds_read2_b32 v[36:37], v36 offset1:1
	v_add_u32_e32 v18, 0x8218, v0
	s_waitcnt lgkmcnt(3)
	v_add_f32_e32 v10, v10, v24
	s_waitcnt lgkmcnt(2)
	v_add_f32_e32 v10, v10, v26
	v_add_f32_e32 v10, v10, v28
	v_add_f32_e32 v10, v10, v38
	v_add_f32_e32 v10, v10, v44
	v_add_f32_e32 v26, v10, v12
	v_add_f32_e32 v10, 0, v19
	v_add_f32_e32 v10, v10, v11
	v_add_f32_e32 v10, v10, v25
	v_add_f32_e32 v10, v10, v27
	v_add_f32_e32 v10, v10, v29
	v_add_f32_e32 v10, v10, v39
	v_add_f32_e32 v10, v10, v45
	v_add_f32_e32 v27, v10, v13
	v_add_f32_e32 v10, 0, v20
	s_waitcnt lgkmcnt(1)
	v_add_f32_e32 v10, v10, v34
	s_waitcnt lgkmcnt(0)
	v_add_f32_e32 v20, v10, v36
	v_add_u32_e32 v10, 0xc310, v0
	ds_read2_b32 v[10:11], v10 offset1:1
	v_add_u32_e32 v12, 0x4118, v0
	v_add_u32_e32 v0, 0xc318, v0
	ds_read2_b32 v[12:13], v12 offset1:1
	ds_read2_b32 v[18:19], v18 offset1:1
	ds_read2_b32 v[24:25], v0 offset1:1
	s_waitcnt lgkmcnt(3)
	v_add_f32_e32 v0, v20, v10
	v_add_f32_e32 v10, 0, v21
	v_add_f32_e32 v10, v10, v35
	v_add_f32_e32 v10, v10, v37
	v_add_f32_e32 v10, v10, v11
	v_add_f32_e32 v10, v10, v31
	v_add_f32_e32 v10, v10, v41
	v_add_f32_e32 v10, v10, v47
	v_add_f32_e32 v20, v10, v15
	v_add_f32_e32 v10, 0, v22
	v_fmamk_f32 v11, v100, 0x3a000000, v214
	s_waitcnt lgkmcnt(2)
	v_add_f32_e32 v10, v10, v12
	v_mul_f32_e32 v12, 0x4b800000, v11
	v_cmp_gt_f32_e64 s[40:41], s65, v11
	s_waitcnt lgkmcnt(1)
	v_add_f32_e32 v10, v10, v18
	s_waitcnt lgkmcnt(0)
	v_add_f32_e32 v10, v10, v24
	v_cndmask_b32_e64 v11, v11, v12, s[40:41]
	v_rsq_f32_e32 v11, v11
	v_add_f32_e32 v10, v10, v32
	v_add_f32_e32 v10, v10, v42
	v_add_f32_e32 v10, v10, v48
	v_mul_f32_e32 v12, 0x45800000, v11
	v_add_f32_e32 v21, v10, v16
	v_add_f32_e32 v10, 0, v23
	v_cndmask_b32_e64 v22, v11, v12, s[40:41]
	v_add_f32_e32 v10, v10, v13
	v_mul_f32_e64 v11, v50, -v22
	v_mul_f32_e64 v12, v51, -v22
	v_add_f32_e32 v10, v10, v19
	v_mul_f32_e32 v11, 0x3fb8aa3b, v11
	v_mul_f32_e32 v12, 0x3fb8aa3b, v12
	v_add_f32_e32 v0, v0, v30
	v_add_f32_e32 v10, v10, v25
	v_exp_f32_e32 v11, v11
	v_exp_f32_e32 v12, v12
	v_add_f32_e32 v0, v0, v40
	v_add_f32_e32 v10, v10, v33
	v_add_f32_e32 v0, v0, v46
	v_add_f32_e32 v10, v10, v43
	v_add_f32_e32 v0, v0, v14
	v_add_f32_e32 v10, v10, v49
	v_lshlrev_b32_e32 v14, 16, v2
	v_and_b32_e32 v15, 0xffff0000, v2
	v_mul_f32_e64 v2, v26, -v22
	v_add_f32_e32 v23, v10, v17
	v_add_f32_e32 v10, 1.0, v11
	v_add_f32_e32 v11, 1.0, v12
	v_lshlrev_b32_e32 v12, 16, v6
	v_and_b32_e32 v13, 0xffff0000, v6
	v_mul_f32_e32 v2, 0x3fb8aa3b, v2
	v_mul_f32_e64 v6, v27, -v22
	v_exp_f32_e32 v2, v2
	v_mul_f32_e32 v6, 0x3fb8aa3b, v6
	v_rcp_f32_e32 v10, v10
	v_rcp_f32_e32 v11, v11
	v_exp_f32_e32 v6, v6
	v_add_f32_e32 v2, 1.0, v2
	v_mul_f32_e64 v0, v0, -v22
	v_pk_fma_f32 v[10:11], v[10:11], v[14:15], v[12:13]
	v_rcp_f32_e32 v14, v2
	v_add_f32_e32 v2, 1.0, v6
	v_rcp_f32_e32 v15, v2
	v_lshlrev_b32_e32 v6, 16, v7
	v_and_b32_e32 v7, 0xffff0000, v7
	v_lshlrev_b32_e32 v2, 16, v3
	v_and_b32_e32 v3, 0xffff0000, v3
	v_pk_fma_f32 v[2:3], v[14:15], v[2:3], v[6:7]
	v_mul_f32_e32 v0, 0x3fb8aa3b, v0
	v_mul_f32_e64 v6, v20, -v22
	v_exp_f32_e32 v0, v0
	v_mul_f32_e32 v6, 0x3fb8aa3b, v6
	v_exp_f32_e32 v15, v6
	v_lshlrev_b32_e32 v18, 16, v4
	v_add_f32_e32 v0, 1.0, v0
	v_rcp_f32_e32 v14, v0
	v_add_f32_e32 v0, 1.0, v15
	v_rcp_f32_e32 v15, v0
	v_mul_f32_e64 v0, v21, -v22
	v_and_b32_e32 v19, 0xffff0000, v4
	v_mul_f32_e32 v0, 0x3fb8aa3b, v0
	v_mul_f32_e64 v4, v23, -v22
	v_exp_f32_e32 v0, v0
	v_mul_f32_e32 v4, 0x3fb8aa3b, v4
	v_exp_f32_e32 v4, v4
	v_lshlrev_b32_e32 v16, 16, v8
	v_and_b32_e32 v17, 0xffff0000, v8
	v_add_f32_e32 v0, 1.0, v0
	v_pk_fma_f32 v[14:15], v[14:15], v[18:19], v[16:17]
	v_rcp_f32_e32 v18, v0
	v_add_f32_e32 v0, 1.0, v4
	v_rcp_f32_e32 v19, v0
	v_pk_mul_f32 v[12:13], v[10:11], v[10:11]
	v_pk_mul_f32 v[6:7], v[2:3], v[2:3]
	v_lshlrev_b32_e32 v8, 16, v9
	v_and_b32_e32 v9, 0xffff0000, v9
	v_lshlrev_b32_e32 v4, 16, v5
	v_and_b32_e32 v5, 0xffff0000, v5
	v_pk_mul_f32 v[16:17], v[14:15], v[14:15]
	v_pk_fma_f32 v[8:9], v[18:19], v[4:5], v[8:9]
	v_add_f32_e32 v0, v6, v7
	v_add_f32_e32 v6, v12, v13
	v_pk_mul_f32 v[4:5], v[8:9], v[8:9]
	v_add_f32_e32 v0, v6, v0
	v_add_f32_e32 v6, v16, v17
	v_add_f32_e32 v0, v0, v6
	v_add_f32_e32 v4, v4, v5
	v_add_f32_e32 v0, v0, v4
	ds_bpermute_b32 v4, v90, v0
	v_cvt_pk_bf16_f32 v5, v2, v3
	v_cvt_pk_bf16_f32 v7, v8, v9
	v_lshl_add_u64 v[8:9], v[82:83], 1, s[48:49]
	s_waitcnt lgkmcnt(0)
	v_add_f32_e32 v0, v0, v4
	ds_bpermute_b32 v6, v91, v0
	v_cvt_pk_bf16_f32 v4, v10, v11
	s_waitcnt lgkmcnt(0)
	v_add_f32_e32 v0, v0, v6
	ds_bpermute_b32 v2, v92, v0
	v_cvt_pk_bf16_f32 v6, v14, v15
	global_store_dwordx4 v[8:9], v[4:7], off
	s_and_saveexec_b64 s[0:1], vcc
	s_cbranch_execz .LBB0_66
	s_waitcnt lgkmcnt(0)
	v_add_f32_e32 v0, v0, v2
	v_lshl_add_u64 v[2:3], v[80:81], 2, s[50:51]
	global_atomic_add_f32 v[2:3], v0, off
	s_branch .LBB0_66

; template <bool GATE>
; __device__ __forceinline__ void sample_gemm_res(LAS unsigned char* lds, const bf16* Amat, const bf16* Bt, const bf16* Hin, bf16* Hout, float* rss_out, const bf16* PP, const float* rss_in, int bid, int tid) {
;     ...
;   for (int tile = bid; tile < 256; tile += (int)gridDim.x) {
;     const int m0 = TP + (tile & 7) * 64, n0 = (tile >> 3) * 64;
;     const bf16x8* ap = (const bf16x8*)(Amat + (size_t)(m0 + lr) * 2048 + wave * 256 + 8 * kg);
;     const bf16x8* bp = (const bf16x8*)(Bt + (size_t)(n0 + lr) * 2048 + wave * 256 + 8 * kg);
;     const int erow = m0 + (tid >> 3); const size_t ep = (size_t)erow * 2048 + n0 + (tid & 7) * 8;
;     const u32x4 hw = *(const u32x4*)(Hin + ep); u32x4 pw = (u32x4){0u, 0u, 0u, 0u}; float rsi = 0.f; if (GATE) { pw = *(const u32x4*)(PP + ep); rsi = rss_in[erow]; }
;     f32x4m acc[4][4];
; #pragma unroll
;     for (int mi = 0; mi < 4; ++mi)
; #pragma unroll
;         for (int ni = 0; ni < 4; ++ni) acc[mi][ni] = (f32x4m){0.f, 0.f, 0.f, 0.f};
; #pragma unroll 2
;     for (int ks = 0; ks < 8; ++ks) { bf16x8 a[4], b[4];
; #pragma unroll
;         for (int q = 0; q < 4; ++q) { a[q] = ap[(size_t)q * 16 * 256 + ks * 4]; b[q] = bp[(size_t)q * 16 * 256 + ks * 4]; }
; #pragma unroll
;         for (int mi = 0; mi < 4; ++mi)
; #pragma unroll
;             for (int ni = 0; ni < 4; ++ni) acc[mi][ni] = __builtin_amdgcn_mfma_f32_16x16x32_bf16(a[mi], b[ni], acc[mi][ni], 0, 0, 0); }
.LBB0_115:
	s_lshl_b32 s0, s6, 6
	s_and_b32 s1, s0, 0x1c0
	v_add_u32_e32 v0, s1, v84
	s_lshl_b32 s0, s6, 3
	v_add_u32_e32 v76, 0x2000, v0
	s_andn2_b32 s0, s0, 63
	v_ashrrev_i32_e32 v77, 31, v76
	v_lshlrev_b64 v[2:3], 11, v[76:77]
	s_ashr_i32 s1, s0, 31
	v_lshl_add_u64 v[78:79], v[2:3], 0, s[0:1]
	v_or_b32_e32 v78, v78, v70
	v_lshl_add_u64 v[2:3], v[78:79], 1, s[46:47]
	global_load_dwordx4 v[2:5], v[2:3], off
	s_and_b32 s0, s3, 0xffffffc0
	v_or_b32_e32 v6, s0, v71
	v_ashrrev_i32_e32 v7, 31, v6
	v_lshlrev_b64 v[6:7], 12, v[6:7]
	s_and_b32 s0, s2, 0x1c0
	v_lshl_add_u64 v[80:81], v[72:73], 0, v[6:7]
	v_add_lshl_u32 v0, v91, s0, 12
	v_mov_b32_e32 v6, 0
	v_lshl_add_u64 v[82:83], v[74:75], 0, v[0:1]
	s_mov_b64 s[4:5], 0
	v_mov_b32_e32 v7, v6
	v_mov_b32_e32 v8, v6
	v_mov_b32_e32 v9, v6
	v_mov_b32_e32 v10, v6
	v_mov_b32_e32 v11, v6
	v_mov_b32_e32 v12, v6
	v_mov_b32_e32 v13, v6
	v_mov_b32_e32 v14, v6
	v_mov_b32_e32 v15, v6
	v_mov_b32_e32 v16, v6
	v_mov_b32_e32 v17, v6
	v_mov_b32_e32 v18, v6
	v_mov_b32_e32 v19, v6
	v_mov_b32_e32 v20, v6
	v_mov_b32_e32 v21, v6
	v_mov_b32_e32 v22, v6
	v_mov_b32_e32 v23, v6
	v_mov_b32_e32 v24, v6
	v_mov_b32_e32 v25, v6
	v_mov_b32_e32 v30, v6
	v_mov_b32_e32 v31, v6
	v_mov_b32_e32 v32, v6
	v_mov_b32_e32 v33, v6
	v_mov_b32_e32 v26, v6
	v_mov_b32_e32 v27, v6
	v_mov_b32_e32 v28, v6
	v_mov_b32_e32 v29, v6
	v_mov_b32_e32 v34, v6
	v_mov_b32_e32 v35, v6
	v_mov_b32_e32 v36, v6
	v_mov_b32_e32 v37, v6
	v_mov_b32_e32 v38, v6
	v_mov_b32_e32 v39, v6
	v_mov_b32_e32 v40, v6
	v_mov_b32_e32 v41, v6
	v_mov_b32_e32 v46, v6
	v_mov_b32_e32 v47, v6
	v_mov_b32_e32 v48, v6
	v_mov_b32_e32 v49, v6
	v_mov_b32_e32 v42, v6
	v_mov_b32_e32 v43, v6
	v_mov_b32_e32 v44, v6
	v_mov_b32_e32 v45, v6
	v_mov_b32_e32 v54, v6
	v_mov_b32_e32 v55, v6
	v_mov_b32_e32 v56, v6
	v_mov_b32_e32 v57, v6
	v_mov_b32_e32 v50, v6
	v_mov_b32_e32 v51, v6
	v_mov_b32_e32 v52, v6
	v_mov_b32_e32 v53, v6
	v_mov_b32_e32 v62, v6
	v_mov_b32_e32 v63, v6
	v_mov_b32_e32 v64, v6
	v_mov_b32_e32 v65, v6
	v_mov_b32_e32 v58, v6
	v_mov_b32_e32 v59, v6
	v_mov_b32_e32 v60, v6
	v_mov_b32_e32 v61, v6
	v_mov_b32_e32 v66, v6
	v_mov_b32_e32 v67, v6
	v_mov_b32_e32 v68, v6
	v_mov_b32_e32 v69, v6
	s_mov_b32 s1, 0x10000
	v_readfirstlane_b32 s8, v82
	v_readfirstlane_b32 s9, v83
	v_readfirstlane_b32 s10, v80
	v_readfirstlane_b32 s11, v81
	s_add_u32 s8, s8, 0x10c00000
	s_addc_u32 s9, s9, 0
	s_add_u32 s10, s10, 0x0
	s_addc_u32 s11, s11, 0
	v_lshrrev_b32_e32 v212, 3, v216
	v_and_b32_e32 v213, 7, v216
	v_xor_b32_e32 v213, v213, v212
	v_lshlrev_b32_e32 v213, 4, v213
	v_lshl_or_b32 v248, v212, 12, v213
	v_and_b32_e32 v212, 15, v216
	v_lshrrev_b32_e32 v213, 4, v216
	v_and_b32_e32 v249, 7, v212
	v_xor_b32_e32 v213, v213, v249
	v_lshlrev_b32_e32 v213, 4, v213
	v_lshl_or_b32 v249, v212, 7, v213
	v_lshrrev_b32_e32 v212, 6, v183
	s_nop 0
	v_readfirstlane_b32 s7, v212
	s_lshl_b32 s7, s7, 14
	v_add_u32_e32 v249, s7, v249
	v_xor_b32_e32 v250, 64, v249
	s_add_i32 m0, s7, 0x0
	s_add_u32 s4, s8, 0x0
	s_addc_u32 s5, s9, 0
	global_load_lds_dwordx4 v248, s[4:5]
	s_add_i32 m0, s7, 0x400
	s_add_u32 s4, s8, 0x8000
	s_addc_u32 s5, s9, 0
	global_load_lds_dwordx4 v248, s[4:5]
	s_add_i32 m0, s7, 0x2000
	s_add_u32 s4, s10, 0x0
	s_addc_u32 s5, s11, 0
	global_load_lds_dwordx4 v248, s[4:5]
	s_add_i32 m0, s7, 0x2400
	s_add_u32 s4, s10, 0x8000
	s_addc_u32 s5, s11, 0
	global_load_lds_dwordx4 v248, s[4:5]
	s_add_i32 m0, s7, 0x800
	s_add_u32 s4, s8, 0x10000
	s_addc_u32 s5, s9, 0
	global_load_lds_dwordx4 v248, s[4:5]
	s_add_i32 m0, s7, 0xc00
	s_add_u32 s4, s8, 0x18000
	s_addc_u32 s5, s9, 0
	global_load_lds_dwordx4 v248, s[4:5]
	s_add_i32 m0, s7, 0x2800
	s_add_u32 s4, s10, 0x10000
	s_addc_u32 s5, s11, 0
	global_load_lds_dwordx4 v248, s[4:5]
	s_add_i32 m0, s7, 0x2c00
	s_add_u32 s4, s10, 0x18000
	s_addc_u32 s5, s11, 0
	global_load_lds_dwordx4 v248, s[4:5]
	s_add_i32 m0, s7, 0x1000
	s_add_u32 s4, s8, 0x20000
	s_addc_u32 s5, s9, 0
	global_load_lds_dwordx4 v248, s[4:5]
	s_add_i32 m0, s7, 0x1400
	s_add_u32 s4, s8, 0x28000
	s_addc_u32 s5, s9, 0
	global_load_lds_dwordx4 v248, s[4:5]
	s_add_i32 m0, s7, 0x3000
	s_add_u32 s4, s10, 0x20000
	s_addc_u32 s5, s11, 0
	global_load_lds_dwordx4 v248, s[4:5]
	s_add_i32 m0, s7, 0x3400
	s_add_u32 s4, s10, 0x28000
	s_addc_u32 s5, s11, 0
	global_load_lds_dwordx4 v248, s[4:5]
	s_add_i32 m0, s7, 0x1800
	s_add_u32 s4, s8, 0x30000
	s_addc_u32 s5, s9, 0
	global_load_lds_dwordx4 v248, s[4:5]
	s_add_i32 m0, s7, 0x1c00
	s_add_u32 s4, s8, 0x38000
	s_addc_u32 s5, s9, 0
	global_load_lds_dwordx4 v248, s[4:5]
	s_add_i32 m0, s7, 0x3800
	s_add_u32 s4, s10, 0x30000
	s_addc_u32 s5, s11, 0
	global_load_lds_dwordx4 v248, s[4:5]
	s_add_i32 m0, s7, 0x3c00
	s_add_u32 s4, s10, 0x38000
	s_addc_u32 s5, s11, 0
	global_load_lds_dwordx4 v248, s[4:5]
	s_waitcnt vmcnt(12)
	ds_read_b128 v[96:99], v249 offset:0
	ds_read_b128 v[100:103], v250 offset:0
	ds_read_b128 v[144:147], v249 offset:8192
	ds_read_b128 v[148:151], v250 offset:8192
	s_waitcnt lgkmcnt(0)
	s_add_i32 m0, s7, 0x0
	s_add_u32 s4, s8, 0x80
	s_addc_u32 s5, s9, 0
	global_load_lds_dwordx4 v248, s[4:5]
	s_add_i32 m0, s7, 0x400
	s_add_u32 s4, s8, 0x8080
	s_addc_u32 s5, s9, 0
	global_load_lds_dwordx4 v248, s[4:5]
	s_add_i32 m0, s7, 0x2000
	s_add_u32 s4, s10, 0x80
	s_addc_u32 s5, s11, 0
	global_load_lds_dwordx4 v248, s[4:5]
	s_add_i32 m0, s7, 0x2400
	s_add_u32 s4, s10, 0x8080
	s_addc_u32 s5, s11, 0
	global_load_lds_dwordx4 v248, s[4:5]
	v_mfma_f32_16x16x32_bf16 v[6:9], v[96:99], v[144:147], v[6:9]
	s_nop 7
	v_mfma_f32_16x16x32_bf16 v[6:9], v[100:103], v[148:151], v[6:9]
	s_waitcnt vmcnt(12)
	ds_read_b128 v[104:107], v249 offset:2048
	ds_read_b128 v[108:111], v250 offset:2048
	ds_read_b128 v[152:155], v249 offset:10240
	ds_read_b128 v[156:159], v250 offset:10240
	s_waitcnt lgkmcnt(0)
; template <bool GATE>
; __device__ __forceinline__ void sample_gemm_res(LAS unsigned char* lds, const bf16* Amat, const bf16* Bt, const bf16* Hin, bf16* Hout, float* rss_out, const bf16* PP, const float* rss_in, int bid, int tid) {
;     ...
;     for (int ks = 0; ks < 8; ++ks) { bf16x8 a[4], b[4];
; #pragma unroll
;         for (int q = 0; q < 4; ++q) { a[q] = ap[(size_t)q * 16 * 256 + ks * 4]; b[q] = bp[(size_t)q * 16 * 256 + ks * 4]; }
; #pragma unroll
;         for (int mi = 0; mi < 4; ++mi)
; #pragma unroll
;             for (int ni = 0; ni < 4; ++ni) acc[mi][ni] = __builtin_amdgcn_mfma_f32_16x16x32_bf16(a[mi], b[ni], acc[mi][ni], 0, 0, 0); }
	s_add_i32 m0, s7, 0x800
	s_add_u32 s4, s8, 0x10080
	s_addc_u32 s5, s9, 0
	global_load_lds_dwordx4 v248, s[4:5]
	s_add_i32 m0, s7, 0xc00
	s_add_u32 s4, s8, 0x18080
	s_addc_u32 s5, s9, 0
	global_load_lds_dwordx4 v248, s[4:5]
	s_add_i32 m0, s7, 0x2800
	s_add_u32 s4, s10, 0x10080
	s_addc_u32 s5, s11, 0
	global_load_lds_dwordx4 v248, s[4:5]
	s_add_i32 m0, s7, 0x2c00
	s_add_u32 s4, s10, 0x18080
	s_addc_u32 s5, s11, 0
	global_load_lds_dwordx4 v248, s[4:5]
	v_mfma_f32_16x16x32_bf16 v[22:25], v[104:107], v[144:147], v[22:25]
	v_mfma_f32_16x16x32_bf16 v[10:13], v[96:99], v[152:155], v[10:13]
	v_mfma_f32_16x16x32_bf16 v[30:33], v[104:107], v[152:155], v[30:33]
	v_mfma_f32_16x16x32_bf16 v[22:25], v[108:111], v[148:151], v[22:25]
	v_mfma_f32_16x16x32_bf16 v[10:13], v[100:103], v[156:159], v[10:13]
	v_mfma_f32_16x16x32_bf16 v[30:33], v[108:111], v[156:159], v[30:33]
	s_waitcnt vmcnt(12)
	ds_read_b128 v[112:115], v249 offset:4096
	ds_read_b128 v[116:119], v250 offset:4096
	ds_read_b128 v[160:163], v249 offset:12288
	ds_read_b128 v[164:167], v250 offset:12288
	s_waitcnt lgkmcnt(0)
	s_add_i32 m0, s7, 0x1000
	s_add_u32 s4, s8, 0x20080
	s_addc_u32 s5, s9, 0
	global_load_lds_dwordx4 v248, s[4:5]
	s_add_i32 m0, s7, 0x1400
	s_add_u32 s4, s8, 0x28080
	s_addc_u32 s5, s9, 0
	global_load_lds_dwordx4 v248, s[4:5]
	s_add_i32 m0, s7, 0x3000
	s_add_u32 s4, s10, 0x20080
	s_addc_u32 s5, s11, 0
	global_load_lds_dwordx4 v248, s[4:5]
	s_add_i32 m0, s7, 0x3400
	s_add_u32 s4, s10, 0x28080
	s_addc_u32 s5, s11, 0
	global_load_lds_dwordx4 v248, s[4:5]
	v_mfma_f32_16x16x32_bf16 v[38:41], v[112:115], v[144:147], v[38:41]
	v_mfma_f32_16x16x32_bf16 v[46:49], v[112:115], v[152:155], v[46:49]
	v_mfma_f32_16x16x32_bf16 v[14:17], v[96:99], v[160:163], v[14:17]
	v_mfma_f32_16x16x32_bf16 v[26:29], v[104:107], v[160:163], v[26:29]
	v_mfma_f32_16x16x32_bf16 v[42:45], v[112:115], v[160:163], v[42:45]
	v_mfma_f32_16x16x32_bf16 v[38:41], v[116:119], v[148:151], v[38:41]
	v_mfma_f32_16x16x32_bf16 v[46:49], v[116:119], v[156:159], v[46:49]
	v_mfma_f32_16x16x32_bf16 v[14:17], v[100:103], v[164:167], v[14:17]
	v_mfma_f32_16x16x32_bf16 v[26:29], v[108:111], v[164:167], v[26:29]
	v_mfma_f32_16x16x32_bf16 v[42:45], v[116:119], v[164:167], v[42:45]
	s_waitcnt vmcnt(12)
	ds_read_b128 v[120:123], v249 offset:6144
	ds_read_b128 v[124:127], v250 offset:6144
	ds_read_b128 v[168:171], v249 offset:14336
	ds_read_b128 v[172:175], v250 offset:14336
	s_waitcnt lgkmcnt(0)
	s_add_i32 m0, s7, 0x1800
	s_add_u32 s4, s8, 0x30080
	s_addc_u32 s5, s9, 0
	global_load_lds_dwordx4 v248, s[4:5]
	s_add_i32 m0, s7, 0x1c00
	s_add_u32 s4, s8, 0x38080
	s_addc_u32 s5, s9, 0
	global_load_lds_dwordx4 v248, s[4:5]
	s_add_i32 m0, s7, 0x3800
	s_add_u32 s4, s10, 0x30080
	s_addc_u32 s5, s11, 0
	global_load_lds_dwordx4 v248, s[4:5]
	s_add_i32 m0, s7, 0x3c00
	s_add_u32 s4, s10, 0x38080
	s_addc_u32 s5, s11, 0
	global_load_lds_dwordx4 v248, s[4:5]
	v_mfma_f32_16x16x32_bf16 v[50:53], v[120:123], v[144:147], v[50:53]
	v_mfma_f32_16x16x32_bf16 v[62:65], v[120:123], v[152:155], v[62:65]
	v_mfma_f32_16x16x32_bf16 v[58:61], v[120:123], v[160:163], v[58:61]
	v_mfma_f32_16x16x32_bf16 v[18:21], v[96:99], v[168:171], v[18:21]
	v_mfma_f32_16x16x32_bf16 v[34:37], v[104:107], v[168:171], v[34:37]
	v_mfma_f32_16x16x32_bf16 v[54:57], v[112:115], v[168:171], v[54:57]
	v_mfma_f32_16x16x32_bf16 v[66:69], v[120:123], v[168:171], v[66:69]
	v_mfma_f32_16x16x32_bf16 v[50:53], v[124:127], v[148:151], v[50:53]
	v_mfma_f32_16x16x32_bf16 v[62:65], v[124:127], v[156:159], v[62:65]
	v_mfma_f32_16x16x32_bf16 v[58:61], v[124:127], v[164:167], v[58:61]
	v_mfma_f32_16x16x32_bf16 v[18:21], v[100:103], v[172:175], v[18:21]
	v_mfma_f32_16x16x32_bf16 v[34:37], v[108:111], v[172:175], v[34:37]
	v_mfma_f32_16x16x32_bf16 v[54:57], v[116:119], v[172:175], v[54:57]
	v_mfma_f32_16x16x32_bf16 v[66:69], v[124:127], v[172:175], v[66:69]
	s_waitcnt vmcnt(12)
	ds_read_b128 v[96:99], v249 offset:0
	ds_read_b128 v[100:103], v250 offset:0
	ds_read_b128 v[144:147], v249 offset:8192
	ds_read_b128 v[148:151], v250 offset:8192
	s_waitcnt lgkmcnt(0)
	s_add_i32 m0, s7, 0x0
	s_add_u32 s4, s8, 0x100
	s_addc_u32 s5, s9, 0
	global_load_lds_dwordx4 v248, s[4:5]
	s_add_i32 m0, s7, 0x400
	s_add_u32 s4, s8, 0x8100
	s_addc_u32 s5, s9, 0
	global_load_lds_dwordx4 v248, s[4:5]
	s_add_i32 m0, s7, 0x2000
	s_add_u32 s4, s10, 0x100
	s_addc_u32 s5, s11, 0
	global_load_lds_dwordx4 v248, s[4:5]
	s_add_i32 m0, s7, 0x2400
	s_add_u32 s4, s10, 0x8100
	s_addc_u32 s5, s11, 0
	global_load_lds_dwordx4 v248, s[4:5]
	v_mfma_f32_16x16x32_bf16 v[6:9], v[96:99], v[144:147], v[6:9]
	s_nop 7
	v_mfma_f32_16x16x32_bf16 v[6:9], v[100:103], v[148:151], v[6:9]
	s_waitcnt vmcnt(12)
	ds_read_b128 v[104:107], v249 offset:2048
	ds_read_b128 v[108:111], v250 offset:2048
	ds_read_b128 v[152:155], v249 offset:10240
	ds_read_b128 v[156:159], v250 offset:10240
	s_waitcnt lgkmcnt(0)
	s_add_i32 m0, s7, 0x800
	s_add_u32 s4, s8, 0x10100
	s_addc_u32 s5, s9, 0
	global_load_lds_dwordx4 v248, s[4:5]
	s_add_i32 m0, s7, 0xc00
	s_add_u32 s4, s8, 0x18100
	s_addc_u32 s5, s9, 0
	global_load_lds_dwordx4 v248, s[4:5]
	s_add_i32 m0, s7, 0x2800
	s_add_u32 s4, s10, 0x10100
	s_addc_u32 s5, s11, 0
	global_load_lds_dwordx4 v248, s[4:5]
	s_add_i32 m0, s7, 0x2c00
	s_add_u32 s4, s10, 0x18100
	s_addc_u32 s5, s11, 0
	global_load_lds_dwordx4 v248, s[4:5]
	v_mfma_f32_16x16x32_bf16 v[22:25], v[104:107], v[144:147], v[22:25]
	v_mfma_f32_16x16x32_bf16 v[10:13], v[96:99], v[152:155], v[10:13]
	v_mfma_f32_16x16x32_bf16 v[30:33], v[104:107], v[152:155], v[30:33]
	v_mfma_f32_16x16x32_bf16 v[22:25], v[108:111], v[148:151], v[22:25]
	v_mfma_f32_16x16x32_bf16 v[10:13], v[100:103], v[156:159], v[10:13]
	v_mfma_f32_16x16x32_bf16 v[30:33], v[108:111], v[156:159], v[30:33]
	s_waitcnt vmcnt(12)
; template <bool GATE>
; __device__ __forceinline__ void sample_gemm_res(LAS unsigned char* lds, const bf16* Amat, const bf16* Bt, const bf16* Hin, bf16* Hout, float* rss_out, const bf16* PP, const float* rss_in, int bid, int tid) {
;     ...
;     for (int ks = 0; ks < 8; ++ks) { bf16x8 a[4], b[4];
; #pragma unroll
;         for (int q = 0; q < 4; ++q) { a[q] = ap[(size_t)q * 16 * 256 + ks * 4]; b[q] = bp[(size_t)q * 16 * 256 + ks * 4]; }
; #pragma unroll
;         for (int mi = 0; mi < 4; ++mi)
; #pragma unroll
;             for (int ni = 0; ni < 4; ++ni) acc[mi][ni] = __builtin_amdgcn_mfma_f32_16x16x32_bf16(a[mi], b[ni], acc[mi][ni], 0, 0, 0); }
	ds_read_b128 v[112:115], v249 offset:4096
	ds_read_b128 v[116:119], v250 offset:4096
	ds_read_b128 v[160:163], v249 offset:12288
	ds_read_b128 v[164:167], v250 offset:12288
	s_waitcnt lgkmcnt(0)
	s_add_i32 m0, s7, 0x1000
	s_add_u32 s4, s8, 0x20100
	s_addc_u32 s5, s9, 0
	global_load_lds_dwordx4 v248, s[4:5]
	s_add_i32 m0, s7, 0x1400
	s_add_u32 s4, s8, 0x28100
	s_addc_u32 s5, s9, 0
	global_load_lds_dwordx4 v248, s[4:5]
	s_add_i32 m0, s7, 0x3000
	s_add_u32 s4, s10, 0x20100
	s_addc_u32 s5, s11, 0
	global_load_lds_dwordx4 v248, s[4:5]
	s_add_i32 m0, s7, 0x3400
	s_add_u32 s4, s10, 0x28100
	s_addc_u32 s5, s11, 0
	global_load_lds_dwordx4 v248, s[4:5]
	v_mfma_f32_16x16x32_bf16 v[38:41], v[112:115], v[144:147], v[38:41]
	v_mfma_f32_16x16x32_bf16 v[46:49], v[112:115], v[152:155], v[46:49]
	v_mfma_f32_16x16x32_bf16 v[14:17], v[96:99], v[160:163], v[14:17]
	v_mfma_f32_16x16x32_bf16 v[26:29], v[104:107], v[160:163], v[26:29]
	v_mfma_f32_16x16x32_bf16 v[42:45], v[112:115], v[160:163], v[42:45]
	v_mfma_f32_16x16x32_bf16 v[38:41], v[116:119], v[148:151], v[38:41]
	v_mfma_f32_16x16x32_bf16 v[46:49], v[116:119], v[156:159], v[46:49]
	v_mfma_f32_16x16x32_bf16 v[14:17], v[100:103], v[164:167], v[14:17]
	v_mfma_f32_16x16x32_bf16 v[26:29], v[108:111], v[164:167], v[26:29]
	v_mfma_f32_16x16x32_bf16 v[42:45], v[116:119], v[164:167], v[42:45]
	s_waitcnt vmcnt(12)
	ds_read_b128 v[120:123], v249 offset:6144
	ds_read_b128 v[124:127], v250 offset:6144
	ds_read_b128 v[168:171], v249 offset:14336
	ds_read_b128 v[172:175], v250 offset:14336
	s_waitcnt lgkmcnt(0)
	s_add_i32 m0, s7, 0x1800
	s_add_u32 s4, s8, 0x30100
	s_addc_u32 s5, s9, 0
	global_load_lds_dwordx4 v248, s[4:5]
	s_add_i32 m0, s7, 0x1c00
	s_add_u32 s4, s8, 0x38100
	s_addc_u32 s5, s9, 0
	global_load_lds_dwordx4 v248, s[4:5]
	s_add_i32 m0, s7, 0x3800
	s_add_u32 s4, s10, 0x30100
	s_addc_u32 s5, s11, 0
	global_load_lds_dwordx4 v248, s[4:5]
	s_add_i32 m0, s7, 0x3c00
	s_add_u32 s4, s10, 0x38100
	s_addc_u32 s5, s11, 0
	global_load_lds_dwordx4 v248, s[4:5]
	v_mfma_f32_16x16x32_bf16 v[50:53], v[120:123], v[144:147], v[50:53]
	v_mfma_f32_16x16x32_bf16 v[62:65], v[120:123], v[152:155], v[62:65]
	v_mfma_f32_16x16x32_bf16 v[58:61], v[120:123], v[160:163], v[58:61]
	v_mfma_f32_16x16x32_bf16 v[18:21], v[96:99], v[168:171], v[18:21]
	v_mfma_f32_16x16x32_bf16 v[34:37], v[104:107], v[168:171], v[34:37]
	v_mfma_f32_16x16x32_bf16 v[54:57], v[112:115], v[168:171], v[54:57]
	v_mfma_f32_16x16x32_bf16 v[66:69], v[120:123], v[168:171], v[66:69]
	v_mfma_f32_16x16x32_bf16 v[50:53], v[124:127], v[148:151], v[50:53]
	v_mfma_f32_16x16x32_bf16 v[62:65], v[124:127], v[156:159], v[62:65]
	v_mfma_f32_16x16x32_bf16 v[58:61], v[124:127], v[164:167], v[58:61]
	v_mfma_f32_16x16x32_bf16 v[18:21], v[100:103], v[172:175], v[18:21]
	v_mfma_f32_16x16x32_bf16 v[34:37], v[108:111], v[172:175], v[34:37]
	v_mfma_f32_16x16x32_bf16 v[54:57], v[116:119], v[172:175], v[54:57]
	v_mfma_f32_16x16x32_bf16 v[66:69], v[124:127], v[172:175], v[66:69]
	s_waitcnt vmcnt(12)
	ds_read_b128 v[96:99], v249 offset:0
	ds_read_b128 v[100:103], v250 offset:0
	ds_read_b128 v[144:147], v249 offset:8192
	ds_read_b128 v[148:151], v250 offset:8192
	s_waitcnt lgkmcnt(0)
	s_add_i32 m0, s7, 0x0
	s_add_u32 s4, s8, 0x180
	s_addc_u32 s5, s9, 0
	global_load_lds_dwordx4 v248, s[4:5]
	s_add_i32 m0, s7, 0x400
	s_add_u32 s4, s8, 0x8180
	s_addc_u32 s5, s9, 0
	global_load_lds_dwordx4 v248, s[4:5]
	s_add_i32 m0, s7, 0x2000
	s_add_u32 s4, s10, 0x180
	s_addc_u32 s5, s11, 0
	global_load_lds_dwordx4 v248, s[4:5]
	s_add_i32 m0, s7, 0x2400
	s_add_u32 s4, s10, 0x8180
	s_addc_u32 s5, s11, 0
	global_load_lds_dwordx4 v248, s[4:5]
	v_mfma_f32_16x16x32_bf16 v[6:9], v[96:99], v[144:147], v[6:9]
	s_nop 7
	v_mfma_f32_16x16x32_bf16 v[6:9], v[100:103], v[148:151], v[6:9]
	s_waitcnt vmcnt(12)
	ds_read_b128 v[104:107], v249 offset:2048
	ds_read_b128 v[108:111], v250 offset:2048
	ds_read_b128 v[152:155], v249 offset:10240
	ds_read_b128 v[156:159], v250 offset:10240
	s_waitcnt lgkmcnt(0)
	s_add_i32 m0, s7, 0x800
	s_add_u32 s4, s8, 0x10180
	s_addc_u32 s5, s9, 0
	global_load_lds_dwordx4 v248, s[4:5]
	s_add_i32 m0, s7, 0xc00
	s_add_u32 s4, s8, 0x18180
	s_addc_u32 s5, s9, 0
	global_load_lds_dwordx4 v248, s[4:5]
	s_add_i32 m0, s7, 0x2800
	s_add_u32 s4, s10, 0x10180
	s_addc_u32 s5, s11, 0
	global_load_lds_dwordx4 v248, s[4:5]
	s_add_i32 m0, s7, 0x2c00
	s_add_u32 s4, s10, 0x18180
	s_addc_u32 s5, s11, 0
	global_load_lds_dwordx4 v248, s[4:5]
	v_mfma_f32_16x16x32_bf16 v[22:25], v[104:107], v[144:147], v[22:25]
	v_mfma_f32_16x16x32_bf16 v[10:13], v[96:99], v[152:155], v[10:13]
	v_mfma_f32_16x16x32_bf16 v[30:33], v[104:107], v[152:155], v[30:33]
	v_mfma_f32_16x16x32_bf16 v[22:25], v[108:111], v[148:151], v[22:25]
	v_mfma_f32_16x16x32_bf16 v[10:13], v[100:103], v[156:159], v[10:13]
	v_mfma_f32_16x16x32_bf16 v[30:33], v[108:111], v[156:159], v[30:33]
	s_waitcnt vmcnt(12)
	ds_read_b128 v[112:115], v249 offset:4096
	ds_read_b128 v[116:119], v250 offset:4096
	ds_read_b128 v[160:163], v249 offset:12288
	ds_read_b128 v[164:167], v250 offset:12288
	s_waitcnt lgkmcnt(0)
; #define LAS __attribute__((address_space(3)))
; template <bool GATE>
; __device__ __forceinline__ void sample_gemm_res(LAS unsigned char* lds, const bf16* Amat, const bf16* Bt, const bf16* Hin, bf16* Hout, float* rss_out, const bf16* PP, const float* rss_in, int bid, int tid) {
;     ...
;     for (int ks = 0; ks < 8; ++ks) { bf16x8 a[4], b[4];
; #pragma unroll
;         for (int q = 0; q < 4; ++q) { a[q] = ap[(size_t)q * 16 * 256 + ks * 4]; b[q] = bp[(size_t)q * 16 * 256 + ks * 4]; }
; #pragma unroll
;         for (int mi = 0; mi < 4; ++mi)
; #pragma unroll
;             for (int ni = 0; ni < 4; ++ni) acc[mi][ni] = __builtin_amdgcn_mfma_f32_16x16x32_bf16(a[mi], b[ni], acc[mi][ni], 0, 0, 0); }
;     LAS float* red = (LAS float*)lds;
;     __syncthreads();
	s_add_i32 m0, s7, 0x1000
	s_add_u32 s4, s8, 0x20180
	s_addc_u32 s5, s9, 0
	global_load_lds_dwordx4 v248, s[4:5]
	s_add_i32 m0, s7, 0x1400
	s_add_u32 s4, s8, 0x28180
	s_addc_u32 s5, s9, 0
	global_load_lds_dwordx4 v248, s[4:5]
	s_add_i32 m0, s7, 0x3000
	s_add_u32 s4, s10, 0x20180
	s_addc_u32 s5, s11, 0
	global_load_lds_dwordx4 v248, s[4:5]
	s_add_i32 m0, s7, 0x3400
	s_add_u32 s4, s10, 0x28180
	s_addc_u32 s5, s11, 0
	global_load_lds_dwordx4 v248, s[4:5]
	v_mfma_f32_16x16x32_bf16 v[38:41], v[112:115], v[144:147], v[38:41]
	v_mfma_f32_16x16x32_bf16 v[46:49], v[112:115], v[152:155], v[46:49]
	v_mfma_f32_16x16x32_bf16 v[14:17], v[96:99], v[160:163], v[14:17]
	v_mfma_f32_16x16x32_bf16 v[26:29], v[104:107], v[160:163], v[26:29]
	v_mfma_f32_16x16x32_bf16 v[42:45], v[112:115], v[160:163], v[42:45]
	v_mfma_f32_16x16x32_bf16 v[38:41], v[116:119], v[148:151], v[38:41]
	v_mfma_f32_16x16x32_bf16 v[46:49], v[116:119], v[156:159], v[46:49]
	v_mfma_f32_16x16x32_bf16 v[14:17], v[100:103], v[164:167], v[14:17]
	v_mfma_f32_16x16x32_bf16 v[26:29], v[108:111], v[164:167], v[26:29]
	v_mfma_f32_16x16x32_bf16 v[42:45], v[116:119], v[164:167], v[42:45]
	s_waitcnt vmcnt(12)
	ds_read_b128 v[120:123], v249 offset:6144
	ds_read_b128 v[124:127], v250 offset:6144
	ds_read_b128 v[168:171], v249 offset:14336
	ds_read_b128 v[172:175], v250 offset:14336
	s_waitcnt lgkmcnt(0)
	s_add_i32 m0, s7, 0x1800
	s_add_u32 s4, s8, 0x30180
	s_addc_u32 s5, s9, 0
	global_load_lds_dwordx4 v248, s[4:5]
	s_add_i32 m0, s7, 0x1c00
	s_add_u32 s4, s8, 0x38180
	s_addc_u32 s5, s9, 0
	global_load_lds_dwordx4 v248, s[4:5]
	s_add_i32 m0, s7, 0x3800
	s_add_u32 s4, s10, 0x30180
	s_addc_u32 s5, s11, 0
	global_load_lds_dwordx4 v248, s[4:5]
	s_add_i32 m0, s7, 0x3c00
	s_add_u32 s4, s10, 0x38180
	s_addc_u32 s5, s11, 0
	global_load_lds_dwordx4 v248, s[4:5]
	v_mfma_f32_16x16x32_bf16 v[50:53], v[120:123], v[144:147], v[50:53]
	v_mfma_f32_16x16x32_bf16 v[62:65], v[120:123], v[152:155], v[62:65]
	v_mfma_f32_16x16x32_bf16 v[58:61], v[120:123], v[160:163], v[58:61]
	v_mfma_f32_16x16x32_bf16 v[18:21], v[96:99], v[168:171], v[18:21]
	v_mfma_f32_16x16x32_bf16 v[34:37], v[104:107], v[168:171], v[34:37]
	v_mfma_f32_16x16x32_bf16 v[54:57], v[112:115], v[168:171], v[54:57]
	v_mfma_f32_16x16x32_bf16 v[66:69], v[120:123], v[168:171], v[66:69]
	v_mfma_f32_16x16x32_bf16 v[50:53], v[124:127], v[148:151], v[50:53]
	v_mfma_f32_16x16x32_bf16 v[62:65], v[124:127], v[156:159], v[62:65]
	v_mfma_f32_16x16x32_bf16 v[58:61], v[124:127], v[164:167], v[58:61]
	v_mfma_f32_16x16x32_bf16 v[18:21], v[100:103], v[172:175], v[18:21]
	v_mfma_f32_16x16x32_bf16 v[34:37], v[108:111], v[172:175], v[34:37]
	v_mfma_f32_16x16x32_bf16 v[54:57], v[116:119], v[172:175], v[54:57]
	v_mfma_f32_16x16x32_bf16 v[66:69], v[124:127], v[172:175], v[66:69]
	s_waitcnt vmcnt(12)
	ds_read_b128 v[96:99], v249 offset:0
	ds_read_b128 v[100:103], v250 offset:0
	ds_read_b128 v[144:147], v249 offset:8192
	ds_read_b128 v[148:151], v250 offset:8192
	s_waitcnt lgkmcnt(0)
	v_mfma_f32_16x16x32_bf16 v[6:9], v[96:99], v[144:147], v[6:9]
	s_nop 7
	v_mfma_f32_16x16x32_bf16 v[6:9], v[100:103], v[148:151], v[6:9]
	s_waitcnt vmcnt(8)
	ds_read_b128 v[104:107], v249 offset:2048
	ds_read_b128 v[108:111], v250 offset:2048
	ds_read_b128 v[152:155], v249 offset:10240
	ds_read_b128 v[156:159], v250 offset:10240
	s_waitcnt lgkmcnt(0)
	v_mfma_f32_16x16x32_bf16 v[22:25], v[104:107], v[144:147], v[22:25]
	v_mfma_f32_16x16x32_bf16 v[10:13], v[96:99], v[152:155], v[10:13]
	v_mfma_f32_16x16x32_bf16 v[30:33], v[104:107], v[152:155], v[30:33]
	v_mfma_f32_16x16x32_bf16 v[22:25], v[108:111], v[148:151], v[22:25]
	v_mfma_f32_16x16x32_bf16 v[10:13], v[100:103], v[156:159], v[10:13]
	v_mfma_f32_16x16x32_bf16 v[30:33], v[108:111], v[156:159], v[30:33]
	s_waitcnt vmcnt(4)
	ds_read_b128 v[112:115], v249 offset:4096
	ds_read_b128 v[116:119], v250 offset:4096
	ds_read_b128 v[160:163], v249 offset:12288
	ds_read_b128 v[164:167], v250 offset:12288
	s_waitcnt lgkmcnt(0)
	v_mfma_f32_16x16x32_bf16 v[38:41], v[112:115], v[144:147], v[38:41]
	v_mfma_f32_16x16x32_bf16 v[46:49], v[112:115], v[152:155], v[46:49]
	v_mfma_f32_16x16x32_bf16 v[14:17], v[96:99], v[160:163], v[14:17]
	v_mfma_f32_16x16x32_bf16 v[26:29], v[104:107], v[160:163], v[26:29]
	v_mfma_f32_16x16x32_bf16 v[42:45], v[112:115], v[160:163], v[42:45]
	v_mfma_f32_16x16x32_bf16 v[38:41], v[116:119], v[148:151], v[38:41]
	v_mfma_f32_16x16x32_bf16 v[46:49], v[116:119], v[156:159], v[46:49]
	v_mfma_f32_16x16x32_bf16 v[14:17], v[100:103], v[164:167], v[14:17]
	v_mfma_f32_16x16x32_bf16 v[26:29], v[108:111], v[164:167], v[26:29]
	v_mfma_f32_16x16x32_bf16 v[42:45], v[116:119], v[164:167], v[42:45]
	s_waitcnt vmcnt(0)
	ds_read_b128 v[120:123], v249 offset:6144
	ds_read_b128 v[124:127], v250 offset:6144
	ds_read_b128 v[168:171], v249 offset:14336
	ds_read_b128 v[172:175], v250 offset:14336
	s_waitcnt lgkmcnt(0)
	v_mfma_f32_16x16x32_bf16 v[50:53], v[120:123], v[144:147], v[50:53]
	v_mfma_f32_16x16x32_bf16 v[62:65], v[120:123], v[152:155], v[62:65]
	v_mfma_f32_16x16x32_bf16 v[58:61], v[120:123], v[160:163], v[58:61]
	v_mfma_f32_16x16x32_bf16 v[18:21], v[96:99], v[168:171], v[18:21]
	v_mfma_f32_16x16x32_bf16 v[34:37], v[104:107], v[168:171], v[34:37]
	v_mfma_f32_16x16x32_bf16 v[54:57], v[112:115], v[168:171], v[54:57]
	v_mfma_f32_16x16x32_bf16 v[66:69], v[120:123], v[168:171], v[66:69]
	v_mfma_f32_16x16x32_bf16 v[50:53], v[124:127], v[148:151], v[50:53]
	v_mfma_f32_16x16x32_bf16 v[62:65], v[124:127], v[156:159], v[62:65]
	v_mfma_f32_16x16x32_bf16 v[58:61], v[124:127], v[164:167], v[58:61]
	v_mfma_f32_16x16x32_bf16 v[18:21], v[100:103], v[172:175], v[18:21]
	v_mfma_f32_16x16x32_bf16 v[34:37], v[108:111], v[172:175], v[34:37]
	v_mfma_f32_16x16x32_bf16 v[54:57], v[116:119], v[172:175], v[54:57]
	v_mfma_f32_16x16x32_bf16 v[66:69], v[124:127], v[172:175], v[66:69]
	s_nop 7
	s_nop 7
	v_add_u32_e32 v0, 0x1000, v89
	s_barrier
; #define LAS __attribute__((address_space(3)))
; __device__ __forceinline__ unsigned cvtpk(float lo, float hi) { f32x2_t v = {lo, hi}; bf16x2_t b = __builtin_convertvector(v, bf16x2_t); return __builtin_bit_cast(unsigned, b); }
; template <bool GATE>
; __device__ __forceinline__ void sample_gemm_res(LAS unsigned char* lds, const bf16* Amat, const bf16* Bt, const bf16* Hin, bf16* Hout, float* rss_out, const bf16* PP, const float* rss_in, int bid, int tid) {
;     ...
;     LAS float* red = (LAS float*)lds;
;     __syncthreads();
; #pragma unroll
;     for (int mi = 0; mi < 4; ++mi)
; #pragma unroll
;         for (int ni = 0; ni < 4; ++ni)
; #pragma unroll
;             for (int i = 0; i < 4; ++i) red[(wave * 64 + 16 * mi + kg * 4 + i) * 65 + 16 * ni + lr] = acc[mi][ni][i];
;     __syncthreads();
;     { const int row = tid >> 3, c8 = (tid & 7) * 8, grow = m0 + row; float v[8];
; #pragma unroll
;       for (int e = 0; e < 8; ++e) { float sacc = 0.f;
; #pragma unroll
;           for (int w = 0; w < 8; ++w) sacc += red[(w * 64 + row) * 65 + c8 + e];
;           v[e] = sacc; }
;       float sc = 1.f; if (GATE) sc = rsqrtf(rsi * (1.f / 2048.f) + 1e-6f);
;       const size_t p = (size_t)grow * 2048 + n0 + c8;
;       const unsigned hws[4] = {hw.x, hw.y, hw.z, hw.w}, pws[4] = {pw.x, pw.y, pw.z, pw.w}; unsigned ow[4]; float sq = 0.f;
; #pragma unroll
;       for (int e2 = 0; e2 < 4; ++e2) { float h0 = __uint_as_float(hws[e2] << 16), h1 = __uint_as_float(hws[e2] & 0xffff0000u);
;           if (GATE) { h0 += __builtin_amdgcn_rcpf(1.f + __expf(-sc * v[2 * e2])) * __uint_as_float(pws[e2] << 16); h1 += __builtin_amdgcn_rcpf(1.f + __expf(-sc * v[2 * e2 + 1])) * __uint_as_float(pws[e2] & 0xffff0000u); }
;           else { h0 += v[2 * e2]; h1 += v[2 * e2 + 1]; }
;           sq += h0 * h0 + h1 * h1; ow[e2] = cvtpk(h0, h1); }
;       *(u32x4*)(Hout + p) = (u32x4){ow[0], ow[1], ow[2], ow[3]};
;       sq += __shfl_xor(sq, 1); sq += __shfl_xor(sq, 2); sq += __shfl_xor(sq, 4);
;       if ((tid & 7) == 0) atomicAdd(rss_out + grow, sq); }
;     __syncthreads();
;   }
	ds_write2_b32 v89, v6, v10 offset1:16
	ds_write2_b32 v89, v7, v11 offset0:65 offset1:81
	ds_write2_b32 v89, v8, v12 offset0:130 offset1:146
	ds_write2_b32 v89, v9, v13 offset0:195 offset1:211
	ds_write2_b32 v89, v14, v18 offset0:32 offset1:48
	ds_write2_b32 v89, v15, v19 offset0:97 offset1:113
	ds_write2_b32 v89, v16, v20 offset0:162 offset1:178
	ds_write2_b32 v89, v17, v21 offset0:227 offset1:243
	ds_write2_b32 v0, v22, v30 offset0:16 offset1:32
	ds_write2_b32 v0, v23, v31 offset0:81 offset1:97
	ds_write2_b32 v0, v24, v32 offset0:146 offset1:162
	ds_write2_b32 v0, v25, v33 offset0:211 offset1:227
	ds_write2_b32 v0, v26, v34 offset0:48 offset1:64
	ds_write2_b32 v0, v27, v35 offset0:113 offset1:129
	ds_write2_b32 v0, v28, v36 offset0:178 offset1:194
	v_add_u32_e32 v0, 0x1200, v89
	ds_write2_b32 v0, v29, v37 offset0:115 offset1:131
	v_add_u32_e32 v0, 0x2000, v89
	ds_write2_b32 v0, v38, v46 offset0:32 offset1:48
	ds_write2_b32 v0, v39, v47 offset0:97 offset1:113
	ds_write2_b32 v0, v40, v48 offset0:162 offset1:178
	ds_write2_b32 v0, v41, v49 offset0:227 offset1:243
	ds_write2_b32 v0, v42, v54 offset0:64 offset1:80
	ds_write2_b32 v0, v43, v55 offset0:129 offset1:145
	ds_write2_b32 v0, v44, v56 offset0:194 offset1:210
	v_add_u32_e32 v0, 0x2400, v89
	ds_write2_b32 v0, v45, v57 offset0:3 offset1:19
	v_add_u32_e32 v0, 0x3000, v89
	v_add_u32_e32 v6, 0x3200, v89
	ds_write2_b32 v0, v50, v62 offset0:48 offset1:64
	ds_write2_b32 v0, v51, v63 offset0:113 offset1:129
	ds_write2_b32 v0, v52, v64 offset0:178 offset1:194
	ds_write2_b32 v6, v53, v65 offset0:115 offset1:131
	ds_write2_b32 v0, v58, v66 offset0:80 offset1:96
	ds_write2_b32 v0, v59, v67 offset0:145 offset1:161
	ds_write2_b32 v0, v60, v68 offset0:210 offset1:226
	v_add_u32_e32 v0, 0x3400, v89
	ds_write2_b32 v0, v61, v69 offset0:19 offset1:35
	v_add_u32_e32 v0, v85, v90
	s_waitcnt lgkmcnt(0)
	s_barrier
	ds_read2_b32 v[6:7], v0 offset1:1
	v_add_u32_e32 v8, 0x4100, v0
	v_add_u32_e32 v10, 0x8200, v0
	v_add_u32_e32 v12, 0xc300, v0
	ds_read2_b32 v[8:9], v8 offset1:1
	ds_read2_b32 v[10:11], v10 offset1:1
	ds_read2_b32 v[12:13], v12 offset1:1
	ds_read2_b32 v[14:15], v0 offset0:2 offset1:3
	ds_read2_b32 v[16:17], v0 offset0:4 offset1:5
	ds_read2_b32 v[18:19], v0 offset0:6 offset1:7
	s_waitcnt lgkmcnt(6)
	v_pk_add_f32 v[6:7], v[6:7], 0 op_sel_hi:[1,0]
	ds_read2_b32 v[20:21], v92 offset1:1
	s_waitcnt lgkmcnt(6)
	v_pk_add_f32 v[6:7], v[6:7], v[8:9]
	ds_read2_b32 v[8:9], v93 offset1:1
	s_waitcnt lgkmcnt(6)
	v_pk_add_f32 v[6:7], v[6:7], v[10:11]
	s_waitcnt lgkmcnt(4)
	v_pk_add_f32 v[14:15], v[14:15], 0 op_sel_hi:[1,0]
	v_pk_add_f32 v[6:7], v[6:7], v[12:13]
	v_add_u32_e32 v42, 0xc308, v0
	s_waitcnt lgkmcnt(1)
	v_pk_add_f32 v[6:7], v[6:7], v[20:21]
	ds_read2_b32 v[10:11], v92 offset0:2 offset1:3
	ds_read2_b32 v[12:13], v92 offset0:4 offset1:5
	ds_read2_b32 v[20:21], v92 offset0:6 offset1:7
	s_waitcnt lgkmcnt(3)
	v_pk_add_f32 v[6:7], v[6:7], v[8:9]
	ds_read2_b32 v[8:9], v94 offset1:1
	ds_read2_b32 v[22:23], v95 offset1:1
	ds_read2_b32 v[24:25], v93 offset0:2 offset1:3
	ds_read2_b32 v[26:27], v93 offset0:4 offset1:5
	ds_read2_b32 v[28:29], v93 offset0:6 offset1:7
	s_waitcnt lgkmcnt(4)
	v_pk_add_f32 v[6:7], v[6:7], v[8:9]
	ds_read2_b32 v[8:9], v94 offset0:2 offset1:3
	ds_read2_b32 v[30:31], v94 offset0:4 offset1:5
	ds_read2_b32 v[32:33], v94 offset0:6 offset1:7
	s_waitcnt lgkmcnt(6)
	v_pk_add_f32 v[6:7], v[6:7], v[22:23]
	v_lshlrev_b32_e32 v22, 16, v2
	v_and_b32_e32 v23, 0xffff0000, v2
	v_add_u32_e32 v2, 0x4108, v0
	ds_read2_b32 v[34:35], v2 offset1:1
	v_add_u32_e32 v2, 0x8208, v0
	ds_read2_b32 v[36:37], v95 offset0:2 offset1:3
	ds_read2_b32 v[38:39], v95 offset0:4 offset1:5
	ds_read2_b32 v[40:41], v95 offset0:6 offset1:7
	v_add_u32_e32 v46, 0x8210, v0
	v_pk_add_f32 v[6:7], v[6:7], v[22:23]
	s_waitcnt lgkmcnt(3)
	v_pk_add_f32 v[14:15], v[14:15], v[34:35]
	ds_read2_b32 v[34:35], v2 offset1:1
	ds_read2_b32 v[42:43], v42 offset1:1
	v_add_u32_e32 v2, 0x4110, v0
	ds_read2_b32 v[44:45], v2 offset1:1
	ds_read2_b32 v[46:47], v46 offset1:1
	v_lshlrev_b32_e32 v2, 16, v3
	s_waitcnt lgkmcnt(3)
	v_pk_add_f32 v[14:15], v[14:15], v[34:35]
	v_and_b32_e32 v3, 0xffff0000, v3
	s_waitcnt lgkmcnt(2)
	v_pk_add_f32 v[14:15], v[14:15], v[42:43]
	v_pk_mul_f32 v[22:23], v[6:7], v[6:7]
	v_pk_add_f32 v[10:11], v[14:15], v[10:11]
	v_add_u32_e32 v14, 0xc310, v0
	ds_read2_b32 v[14:15], v14 offset1:1
	v_pk_add_f32 v[10:11], v[10:11], v[24:25]
	v_add_u32_e32 v24, 0x8218, v0
	v_pk_add_f32 v[8:9], v[10:11], v[8:9]
	v_pk_add_f32 v[10:11], v[16:17], 0 op_sel_hi:[1,0]
	v_add_u32_e32 v16, 0x4118, v0
	s_waitcnt lgkmcnt(2)
	v_pk_add_f32 v[10:11], v[10:11], v[44:45]
	v_add_u32_e32 v0, 0xc318, v0
	ds_read2_b32 v[16:17], v16 offset1:1
	ds_read2_b32 v[24:25], v24 offset1:1
	ds_read2_b32 v[34:35], v0 offset1:1
	s_waitcnt lgkmcnt(4)
	v_pk_add_f32 v[10:11], v[10:11], v[46:47]
	v_pk_add_f32 v[8:9], v[8:9], v[36:37]
	s_waitcnt lgkmcnt(3)
	v_pk_add_f32 v[10:11], v[10:11], v[14:15]
	v_pk_add_f32 v[14:15], v[18:19], 0 op_sel_hi:[1,0]
	v_pk_add_f32 v[10:11], v[10:11], v[12:13]
	s_waitcnt lgkmcnt(2)
	v_pk_add_f32 v[14:15], v[14:15], v[16:17]
	v_pk_add_f32 v[10:11], v[10:11], v[26:27]
	s_waitcnt lgkmcnt(1)
	v_pk_add_f32 v[14:15], v[14:15], v[24:25]
	v_pk_add_f32 v[10:11], v[10:11], v[30:31]
	s_waitcnt lgkmcnt(0)
	v_pk_add_f32 v[14:15], v[14:15], v[34:35]
	v_pk_add_f32 v[2:3], v[8:9], v[2:3]
	v_pk_add_f32 v[14:15], v[14:15], v[20:21]
	v_pk_add_f32 v[10:11], v[10:11], v[38:39]
	v_pk_add_f32 v[14:15], v[14:15], v[28:29]
	v_lshlrev_b32_e32 v12, 16, v4
	v_and_b32_e32 v13, 0xffff0000, v4
	v_pk_add_f32 v[14:15], v[14:15], v[32:33]
	v_pk_mul_f32 v[8:9], v[2:3], v[2:3]
	v_pk_add_f32 v[10:11], v[10:11], v[12:13]
	v_pk_add_f32 v[14:15], v[14:15], v[40:41]
	v_lshlrev_b32_e32 v4, 16, v5
	v_and_b32_e32 v5, 0xffff0000, v5
	v_pk_mul_f32 v[12:13], v[10:11], v[10:11]
	v_pk_add_f32 v[14:15], v[14:15], v[4:5]
	v_add_f32_e32 v0, v8, v9
	v_add_f32_e32 v8, v22, v23
	v_pk_mul_f32 v[4:5], v[14:15], v[14:15]
	v_add_f32_e32 v0, v8, v0
	v_add_f32_e32 v8, v12, v13
	v_add_f32_e32 v0, v0, v8
	v_add_f32_e32 v4, v4, v5
	v_add_f32_e32 v0, v0, v4
	ds_bpermute_b32 v4, v86, v0
	v_cvt_pk_bf16_f32 v5, v2, v3
	s_waitcnt lgkmcnt(0)
	v_add_f32_e32 v0, v0, v4
	ds_bpermute_b32 v8, v87, v0
	v_cvt_pk_bf16_f32 v4, v6, v7
	v_cvt_pk_bf16_f32 v6, v10, v11
	v_cvt_pk_bf16_f32 v7, v14, v15
	s_waitcnt lgkmcnt(0)
	v_add_f32_e32 v0, v0, v8
	ds_bpermute_b32 v2, v88, v0
	v_lshl_add_u64 v[8:9], v[78:79], 1, s[48:49]
	global_store_dwordx4 v[8:9], v[4:7], off
	s_and_saveexec_b64 s[0:1], vcc
	s_cbranch_execz .LBB0_114
	s_waitcnt lgkmcnt(0)
	v_add_f32_e32 v0, v0, v2
	v_lshl_add_u64 v[2:3], v[76:77], 2, s[50:51]
	global_atomic_add_f32 v[2:3], v0, off
	s_branch .LBB0_114

; __device__ __forceinline__ unsigned xb_ld(unsigned* p)              { return __hip_atomic_load(p, __ATOMIC_RELAXED, __HIP_MEMORY_SCOPE_AGENT); }
; __device__ __forceinline__ unsigned xb_add(unsigned* p, unsigned v) { return __hip_atomic_fetch_add(p, v, __ATOMIC_RELAXED, __HIP_MEMORY_SCOPE_AGENT); }
; #define XB_SPIN(cond, bar) do { unsigned _sp = 0; while (cond) { __builtin_amdgcn_s_sleep(1); \
;     if ((++_sp & 255u) == 0u) { if (xb_ld(&(bar)[XB_TMO])) break; if (_sp > XB_SPIN_CAP) { atomicAdd(&(bar)[XB_TMO], 1u); break; } } } } while (0)
; __device__ __forceinline__ void xcd_barrier(const XcdBarrier& b) {
;     ...
;         if (old + 1u == (gen + 1u) * nloc) {
;             __builtin_amdgcn_fence(__ATOMIC_RELEASE, "agent");
;             asm volatile("s_waitcnt vmcnt(0)" ::: "memory");
;             const unsigned og = xb_add(&bar[XB_TOP], 1u);
;             const unsigned tg = og / nx;
;             if (og + 1u == (tg + 1u) * nx) xb_add(&bar[XB_TOPGEN], 1u);
;             else XB_SPIN(xb_ld(&bar[XB_TOPGEN]) == tg, bar);
;             __builtin_amdgcn_fence(__ATOMIC_ACQUIRE, "agent");
;             xb_add(&bar[XB_XGEN(b.x)], 1u);
;             asm volatile("s_waitcnt vmcnt(0)" ::: "memory");
.LBB0_1027:
	s_or_b64 exec, exec, s[2:3]
	v_cvt_f32_u32_e32 v5, v3
	s_waitcnt vmcnt(0)
	v_readfirstlane_b32 s2, v4
	v_sub_u32_e32 v4, 0, v3
	v_rcp_iflag_f32_e32 v5, v5
	v_add_u32_e32 v6, s2, v0
	v_mul_f32_e32 v5, 0x4f7ffffe, v5
	v_cvt_u32_f32_e32 v5, v5
	v_mul_lo_u32 v0, v4, v5
	v_mul_hi_u32 v0, v5, v0
	v_add_u32_e32 v0, v5, v0
	v_mul_hi_u32 v0, v6, v0
	v_mul_lo_u32 v4, v0, v3
	v_sub_u32_e32 v4, v6, v4
	v_add_u32_e32 v5, 1, v0
	v_cmp_ge_u32_e32 vcc, v4, v3
	s_nop 1
	v_cndmask_b32_e32 v0, v0, v5, vcc
	v_sub_u32_e32 v5, v4, v3
	v_cndmask_b32_e32 v4, v4, v5, vcc
	v_add_u32_e32 v5, 1, v0
	v_cmp_ge_u32_e32 vcc, v4, v3
	v_add_u32_e32 v4, 1, v6
	s_nop 0
	v_cndmask_b32_e32 v0, v0, v5, vcc
	v_mul_lo_u32 v5, v3, v0
	v_add_u32_e32 v3, v5, v3
	v_add_u32_e32 v7, 1, v0
	v_mul_lo_u32 v7, v7, v2
	v_cmp_ne_u32_e32 vcc, v4, v3
	s_mov_b64 s[2:3], 0
	s_cbranch_vccnz .Lxb_wait
	buffer_wbl2 sc1
	v_readlane_b32 s6, v251, 7
	v_readlane_b32 s7, v251, 8
	v_mov_b32_e32 v8, 1
	s_nop 3
	s_add_u32 s6, s6, 0x2200
	s_addc_u32 s7, s7, 0
	s_nop 0
	s_waitcnt vmcnt(0) lgkmcnt(0)
	global_atomic_add v1, v8, s[6:7]
	global_atomic_add v1, v8, s[6:7] offset:256
	global_atomic_add v1, v8, s[6:7] offset:512
	global_atomic_add v1, v8, s[6:7] offset:768
	global_atomic_add v1, v8, s[6:7] offset:1024
	global_atomic_add v1, v8, s[6:7] offset:1280
	global_atomic_add v1, v8, s[6:7] offset:1536
	global_atomic_add v1, v8, s[6:7] offset:1792
	global_atomic_add v1, v8, s[6:7] offset:2048
	global_atomic_add v1, v8, s[6:7] offset:2304
	global_atomic_add v1, v8, s[6:7] offset:2560
	global_atomic_add v1, v8, s[6:7] offset:2816
	global_atomic_add v1, v8, s[6:7] offset:3072
	global_atomic_add v1, v8, s[6:7] offset:3328
	global_atomic_add v1, v8, s[6:7] offset:3584
	global_atomic_add v1, v8, s[6:7] offset:3840
